# adds: MLA weight staging batched (9 loads in flight), prologue transposes issue all 64 weight+gain loads before one wait (3 call sites), grid barrier after the final norm removed (same wave owns the s
# speedup vs baseline: 1.0302x; 1.0207x over previous
; __device__ __forceinline__ void transpose_item(const float* W, int K, int N, bf16_t* WT, int n0d, int n0s, float scale, int k0, float* scr, int lane, bool gperm = false, const float* kgain = nullptr) {
;     ...
;     } else if (n0s >= 0) {
; #pragma unroll
;         for (int i = 0; i < 32; ++i) { const int kk = 2 * i + (lane >> 5); scr[kk * 33 + (lane & 31)] = W[(size_t)(k0 + kk) * N + n0s + (lane & 31)] * (kgain ? scale * kgain[k0 + kk] : scale); }
;     } else {
; #pragma unroll
;         for (int i = 0; i < 32; ++i) { const int kk = 2 * i + (lane >> 5); scr[kk * 33 + (lane & 31)] = 0.f; }
;     }
;     __builtin_amdgcn_wave_barrier(); asm volatile("s_waitcnt lgkmcnt(0)" ::: "memory");
; __device__ __forceinline__ void prologue(const Args& a, unsigned char* ws, char* lds, int gw, int NGW, int wave, int lane) {
;     ...
;         if (r < I_FI) { const int nb = r % (NUG / 32), kb = r / (NUG / 32);
;             const int n0d = nb * 32, src0 = ((n0d >> 7) & 1) * FF + (n0d >> 8) * 128 + (n0d & 127);
;             transpose_item(a.in[19] + (size_t)l * DM * NUG, DM, NUG, (bf16_t*)(ws + WS_WFI) + (size_t)l * NUG * DM, n0d, src0, 1.f, kb * 64, scr, lane, false, a.in[18] + l * DM); continue; }
.LBB0_24:
	s_andn2_b64 vcc, exec, s[0:1]
	s_cbranch_vccnz .LBB0_90
	s_add_i32 s0, s18, 0xef00
	s_and_b32 s1, s0, 0xffff
	s_mul_i32 s1, s1, 0xba2f
	s_lshr_b32 s1, s1, 23
	s_mul_i32 s12, s1, 0xb0
	s_sub_i32 s0, s0, s12
	s_and_b32 s15, s0, 0xffff
	s_lshl_b32 s12, s15, 5
	s_bfe_i32 s0, s0, 0x10002
	s_lshl_b32 s15, s15, 4
	s_and_b32 s0, s0, 0xb00
	s_and_b32 s15, s15, 0xf80
	s_add_i32 s0, s0, s15
	s_and_b32 s15, s12, 0x60
	v_readlane_b32 s52, v253, 32
	s_or_b32 s19, s0, s15
	s_mul_i32 s15, s14, 0x1600000
	v_readlane_b32 s58, v253, 38
	s_mul_hi_i32 s0, s14, 0x1600000
	v_readlane_b32 s59, v253, 39
	s_add_u32 s20, s58, s15
	s_addc_u32 s21, s59, s0
	s_lshl_b32 s0, s14, 10
	s_lshl_b32 s15, s1, 6
	s_ashr_i32 s1, s0, 31
	v_readlane_b32 s56, v253, 36
	s_lshl_b64 s[0:1], s[0:1], 2
	v_readlane_b32 s57, v253, 37
	s_add_u32 s16, s56, s0
	s_addc_u32 s17, s57, s1
	s_lshl_b32 s0, s19, 2
	s_add_u32 s0, s20, s0
	s_addc_u32 s1, s21, 0
	v_lshlrev_b32_e32 v6, 2, v4
	v_lshl_add_u64 v[10:11], s[0:1], 0, v[6:7]
	v_or_b32_e32 v13, s15, v2
	v_mad_u64_u32 v[88:89], s[0:1], v13, s47, v[10:11]
	global_load_dword v126, v[88:89], off
	v_or_b32_e32 v13, s15, v14
	v_mad_u64_u32 v[88:89], s[20:21], v13, s47, v[10:11]
	global_load_dword v127, v[88:89], off
	v_or_b32_e32 v13, s15, v16
	v_mad_u64_u32 v[88:89], s[20:21], v13, s47, v[10:11]
	global_load_dword v128, v[88:89], off
	v_or_b32_e32 v13, s15, v18
	v_mad_u64_u32 v[88:89], s[20:21], v13, s47, v[10:11]
	global_load_dword v129, v[88:89], off
	v_or_b32_e32 v13, s15, v20
	v_mad_u64_u32 v[88:89], s[20:21], v13, s47, v[10:11]
	global_load_dword v130, v[88:89], off
	v_or_b32_e32 v13, s15, v22
	v_mad_u64_u32 v[88:89], s[20:21], v13, s47, v[10:11]
	global_load_dword v131, v[88:89], off
	v_or_b32_e32 v13, s15, v24
	v_mad_u64_u32 v[88:89], s[20:21], v13, s47, v[10:11]
	global_load_dword v132, v[88:89], off
	v_or_b32_e32 v13, s15, v26
	v_mad_u64_u32 v[88:89], s[20:21], v13, s47, v[10:11]
	global_load_dword v133, v[88:89], off
	v_or_b32_e32 v13, s15, v28
	v_mad_u64_u32 v[88:89], s[20:21], v13, s47, v[10:11]
	global_load_dword v134, v[88:89], off
	v_or_b32_e32 v13, s15, v30
	v_mad_u64_u32 v[88:89], s[20:21], v13, s47, v[10:11]
	global_load_dword v135, v[88:89], off
	v_or_b32_e32 v13, s15, v32
	v_mad_u64_u32 v[88:89], s[20:21], v13, s47, v[10:11]
	global_load_dword v136, v[88:89], off
	v_or_b32_e32 v13, s15, v34
	v_mad_u64_u32 v[88:89], s[20:21], v13, s47, v[10:11]
	global_load_dword v137, v[88:89], off
	v_or_b32_e32 v13, s15, v36
	v_mad_u64_u32 v[88:89], s[20:21], v13, s47, v[10:11]
	global_load_dword v138, v[88:89], off
	v_or_b32_e32 v13, s15, v38
	v_mad_u64_u32 v[88:89], s[20:21], v13, s47, v[10:11]
	global_load_dword v139, v[88:89], off
	v_or_b32_e32 v13, s15, v40
	v_mad_u64_u32 v[88:89], s[20:21], v13, s47, v[10:11]
	global_load_dword v140, v[88:89], off
	v_or_b32_e32 v13, s15, v42
	v_mad_u64_u32 v[88:89], s[20:21], v13, s47, v[10:11]
	global_load_dword v141, v[88:89], off
	v_or_b32_e32 v13, s15, v44
	v_mad_u64_u32 v[88:89], s[20:21], v13, s47, v[10:11]
	global_load_dword v142, v[88:89], off
	v_or_b32_e32 v13, s15, v46
	v_mad_u64_u32 v[88:89], s[20:21], v13, s47, v[10:11]
	global_load_dword v143, v[88:89], off
	v_or_b32_e32 v13, s15, v48
	v_mad_u64_u32 v[88:89], s[20:21], v13, s47, v[10:11]
	global_load_dword v144, v[88:89], off
	v_or_b32_e32 v13, s15, v50
	v_mad_u64_u32 v[88:89], s[20:21], v13, s47, v[10:11]
	global_load_dword v145, v[88:89], off
	v_or_b32_e32 v13, s15, v52
	v_mad_u64_u32 v[88:89], s[20:21], v13, s47, v[10:11]
	global_load_dword v146, v[88:89], off
	v_or_b32_e32 v13, s15, v54
	v_mad_u64_u32 v[88:89], s[20:21], v13, s47, v[10:11]
	global_load_dword v147, v[88:89], off
	v_or_b32_e32 v13, s15, v56
	v_mad_u64_u32 v[88:89], s[20:21], v13, s47, v[10:11]
	global_load_dword v148, v[88:89], off
	v_or_b32_e32 v13, s15, v58
	v_mad_u64_u32 v[88:89], s[20:21], v13, s47, v[10:11]
	global_load_dword v149, v[88:89], off
	v_or_b32_e32 v13, s15, v60
	v_mad_u64_u32 v[88:89], s[20:21], v13, s47, v[10:11]
	global_load_dword v150, v[88:89], off
	v_or_b32_e32 v13, s15, v62
	v_mad_u64_u32 v[88:89], s[20:21], v13, s47, v[10:11]
	global_load_dword v151, v[88:89], off
	v_or_b32_e32 v13, s15, v64
	v_mad_u64_u32 v[88:89], s[20:21], v13, s47, v[10:11]
	global_load_dword v152, v[88:89], off
	v_or_b32_e32 v13, s15, v71
	v_mad_u64_u32 v[88:89], s[20:21], v13, s47, v[10:11]
	global_load_dword v153, v[88:89], off
	v_or_b32_e32 v13, s15, v73
	v_mad_u64_u32 v[88:89], s[20:21], v13, s47, v[10:11]
	global_load_dword v154, v[88:89], off
	v_or_b32_e32 v13, s15, v75
	v_mad_u64_u32 v[88:89], s[20:21], v13, s47, v[10:11]
	global_load_dword v155, v[88:89], off
	v_or_b32_e32 v13, s15, v77
	v_mad_u64_u32 v[88:89], s[20:21], v13, s47, v[10:11]
	global_load_dword v156, v[88:89], off
	v_or_b32_e32 v13, s15, v79
	v_mad_u64_u32 v[88:89], s[20:21], v13, s47, v[10:11]
	global_load_dword v157, v[88:89], off
	v_cndmask_b32_e64 v88, 0, 1, s[8:9]
	v_cmp_ne_u32_e64 s[0:1], 1, v88
	v_readlane_b32 s53, v253, 33
	v_readlane_b32 s54, v253, 34
	v_readlane_b32 s55, v253, 35
	v_readlane_b32 s60, v253, 40
	v_readlane_b32 s61, v253, 41
	v_readlane_b32 s62, v253, 42
	v_readlane_b32 s63, v253, 43
	v_readlane_b32 s64, v253, 44
	v_readlane_b32 s65, v253, 45
	v_readlane_b32 s66, v253, 46
	v_readlane_b32 s67, v253, 47
	v_mov_b32_e32 v194, 1.0
	v_mov_b32_e32 v195, 1.0
	v_mov_b32_e32 v196, 1.0
	v_mov_b32_e32 v197, 1.0
	v_mov_b32_e32 v198, 1.0
	v_mov_b32_e32 v199, 1.0
	v_mov_b32_e32 v200, 1.0
	v_mov_b32_e32 v201, 1.0
	v_mov_b32_e32 v202, 1.0
	v_mov_b32_e32 v203, 1.0
	v_mov_b32_e32 v204, 1.0
	v_mov_b32_e32 v205, 1.0
	v_mov_b32_e32 v206, 1.0
	v_mov_b32_e32 v207, 1.0
	v_mov_b32_e32 v208, 1.0
	v_mov_b32_e32 v209, 1.0
	v_mov_b32_e32 v210, 1.0
	v_mov_b32_e32 v211, 1.0
	v_mov_b32_e32 v212, 1.0
	v_mov_b32_e32 v213, 1.0
	v_mov_b32_e32 v214, 1.0
	v_mov_b32_e32 v215, 1.0
	v_mov_b32_e32 v216, 1.0
	v_mov_b32_e32 v217, 1.0
	v_mov_b32_e32 v218, 1.0
	v_mov_b32_e32 v219, 1.0
	v_mov_b32_e32 v220, 1.0
	v_mov_b32_e32 v221, 1.0
	v_mov_b32_e32 v222, 1.0
	v_mov_b32_e32 v223, 1.0
	v_mov_b32_e32 v224, 1.0
	v_mov_b32_e32 v225, 1.0
	s_and_b64 vcc, exec, s[0:1]
	s_cbranch_vccnz .Lpro1_nokg
; __device__ __forceinline__ unsigned cvt_pk_bf16(float lo, float hi) { typedef float f2 __attribute__((ext_vector_type(2))); typedef __bf16 b2 __attribute__((ext_vector_type(2))); f2 v = {lo, hi}; b2 b = __builtin_convertvector(v, b2); return __builtin_bit_cast(unsigned, b); }
; __device__ __forceinline__ void transpose_item(const float* W, int K, int N, bf16_t* WT, int n0d, int n0s, float scale, int k0, float* scr, int lane, bool gperm = false, const float* kgain = nullptr) {
;     ...
;         for (int i = 0; i < 32; ++i) { const int kk = 2 * i + (lane >> 5); scr[kk * 33 + (lane & 31)] = W[(size_t)(k0 + kk) * N + n0s + (lane & 31)] * (kgain ? scale * kgain[k0 + kk] : scale); }
;     } else {
; #pragma unroll
;         for (int i = 0; i < 32; ++i) { const int kk = 2 * i + (lane >> 5); scr[kk * 33 + (lane & 31)] = 0.f; }
;     }
;     __builtin_amdgcn_wave_barrier(); asm volatile("s_waitcnt lgkmcnt(0)" ::: "memory");
;     const int c = lane & 7;
; #pragma unroll
;     for (int j = 0; j < 4; ++j) { const int n = (lane >> 3) + 8 * j; const float* s = scr + (8 * c) * 33 + n;
;         u32x4 o; o.x = cvt_pk_bf16(s[0 * 33], s[1 * 33]); o.y = cvt_pk_bf16(s[2 * 33], s[3 * 33]); o.z = cvt_pk_bf16(s[4 * 33], s[5 * 33]); o.w = cvt_pk_bf16(s[6 * 33], s[7 * 33]);
;         *(u32x4*)(WT + (size_t)(n0d + n) * K + k0 + 8 * c) = o; }
	v_add_lshl_u32 v6, v2, s15, 2
	global_load_dword v194, v6, s[16:17]
	global_load_dword v195, v6, s[16:17] offset:8
	global_load_dword v196, v6, s[16:17] offset:16
	global_load_dword v197, v6, s[16:17] offset:24
	global_load_dword v198, v6, s[16:17] offset:32
	global_load_dword v199, v6, s[16:17] offset:40
	global_load_dword v200, v6, s[16:17] offset:48
	global_load_dword v201, v6, s[16:17] offset:56
	global_load_dword v202, v6, s[16:17] offset:64
	global_load_dword v203, v6, s[16:17] offset:72
	global_load_dword v204, v6, s[16:17] offset:80
	global_load_dword v205, v6, s[16:17] offset:88
	global_load_dword v206, v6, s[16:17] offset:96
	global_load_dword v207, v6, s[16:17] offset:104
	global_load_dword v208, v6, s[16:17] offset:112
	global_load_dword v209, v6, s[16:17] offset:120
	global_load_dword v210, v6, s[16:17] offset:128
	global_load_dword v211, v6, s[16:17] offset:136
	global_load_dword v212, v6, s[16:17] offset:144
	global_load_dword v213, v6, s[16:17] offset:152
	global_load_dword v214, v6, s[16:17] offset:160
	global_load_dword v215, v6, s[16:17] offset:168
	global_load_dword v216, v6, s[16:17] offset:176
	global_load_dword v217, v6, s[16:17] offset:184
	global_load_dword v218, v6, s[16:17] offset:192
	global_load_dword v219, v6, s[16:17] offset:200
	global_load_dword v220, v6, s[16:17] offset:208
	global_load_dword v221, v6, s[16:17] offset:216
	global_load_dword v222, v6, s[16:17] offset:224
	global_load_dword v223, v6, s[16:17] offset:232
	global_load_dword v224, v6, s[16:17] offset:240
	global_load_dword v225, v6, s[16:17] offset:248
.Lpro1_nokg:
	s_waitcnt vmcnt(0)
	v_mul_f32_e32 v126, v126, v194
	ds_write_b32 v9, v126
	v_mul_f32_e32 v127, v127, v195
	ds_write_b32 v15, v127
	v_mul_f32_e32 v128, v128, v196
	ds_write_b32 v17, v128
	v_mul_f32_e32 v129, v129, v197
	ds_write_b32 v19, v129
	v_mul_f32_e32 v130, v130, v198
	ds_write_b32 v21, v130
	v_mul_f32_e32 v131, v131, v199
	ds_write_b32 v23, v131
	v_mul_f32_e32 v132, v132, v200
	ds_write_b32 v25, v132
	v_mul_f32_e32 v133, v133, v201
	ds_write_b32 v27, v133
	v_mul_f32_e32 v134, v134, v202
	ds_write_b32 v29, v134
	v_mul_f32_e32 v135, v135, v203
	ds_write_b32 v31, v135
	v_mul_f32_e32 v136, v136, v204
	ds_write_b32 v33, v136
	v_mul_f32_e32 v137, v137, v205
	ds_write_b32 v35, v137
	v_mul_f32_e32 v138, v138, v206
	ds_write_b32 v37, v138
	v_mul_f32_e32 v139, v139, v207
	ds_write_b32 v39, v139
	v_mul_f32_e32 v140, v140, v208
	ds_write_b32 v41, v140
	v_mul_f32_e32 v141, v141, v209
	ds_write_b32 v43, v141
	v_mul_f32_e32 v142, v142, v210
	ds_write_b32 v45, v142
	v_mul_f32_e32 v143, v143, v211
	ds_write_b32 v47, v143
	v_mul_f32_e32 v144, v144, v212
	ds_write_b32 v49, v144
	v_mul_f32_e32 v145, v145, v213
	ds_write_b32 v51, v145
	v_mul_f32_e32 v146, v146, v214
	ds_write_b32 v53, v146
	v_mul_f32_e32 v147, v147, v215
	ds_write_b32 v55, v147
	v_mul_f32_e32 v148, v148, v216
	ds_write_b32 v57, v148
	v_mul_f32_e32 v149, v149, v217
	ds_write_b32 v59, v149
	v_mul_f32_e32 v150, v150, v218
	ds_write_b32 v61, v150
	v_mul_f32_e32 v151, v151, v219
	ds_write_b32 v63, v151
	v_mul_f32_e32 v152, v152, v220
	ds_write_b32 v65, v152
	v_mul_f32_e32 v153, v153, v221
	ds_write_b32 v72, v153
	v_mul_f32_e32 v154, v154, v222
	ds_write_b32 v74, v154
	v_mul_f32_e32 v155, v155, v223
	ds_write_b32 v76, v155
	v_mul_f32_e32 v156, v156, v224
	ds_write_b32 v78, v156
	v_mul_f32_e32 v157, v157, v225
	ds_write_b32 v80, v157
	s_mul_i32 s1, s14, 0xb00000
	s_mul_hi_i32 s0, s14, 0xb00000
	s_add_u32 s1, s33, s1
	s_waitcnt lgkmcnt(0)
	s_addc_u32 s16, s34, s0
	s_lshl_b32 s0, s15, 1
	ds_read_b32 v10, v67
	ds_read_b32 v11, v67 offset:132
	ds_read_b32 v12, v67 offset:264
	ds_read_b32 v13, v67 offset:396
	ds_read_b32 v90, v67 offset:528
	ds_read_b32 v91, v67 offset:660
	ds_read_b32 v92, v67 offset:792
	ds_read_b32 v93, v67 offset:924
	s_add_u32 s0, s1, s0
	s_addc_u32 s1, s16, 0
	v_lshlrev_b32_e32 v6, 1, v8
	v_lshl_add_u64 v[88:89], s[0:1], 0, v[6:7]
	v_or_b32_e32 v6, s12, v66
	v_lshlrev_b32_e32 v6, 11, v6
	s_waitcnt lgkmcnt(0)
	v_cvt_pk_bf16_f32 v10, v10, v11
	v_cvt_pk_bf16_f32 v11, v12, v13
	v_cvt_pk_bf16_f32 v12, v90, v91
	v_cvt_pk_bf16_f32 v13, v92, v93
	v_lshl_add_u64 v[90:91], v[88:89], 0, v[6:7]
	flat_store_dwordx4 v[90:91], v[10:13]
	ds_read_b32 v6, v67 offset:32
	ds_read_b32 v10, v67 offset:164
	ds_read_b32 v11, v67 offset:296
	ds_read_b32 v12, v67 offset:428
	ds_read_b32 v13, v67 offset:560
	ds_read_b32 v90, v67 offset:692
	ds_read_b32 v91, v67 offset:824
	ds_read_b32 v92, v67 offset:956
	s_waitcnt lgkmcnt(0)
	v_cvt_pk_bf16_f32 v10, v6, v10
	v_or_b32_e32 v6, s12, v81
	v_lshlrev_b32_e32 v6, 11, v6
	v_cvt_pk_bf16_f32 v11, v11, v12
	v_cvt_pk_bf16_f32 v12, v13, v90
	v_cvt_pk_bf16_f32 v13, v91, v92
	v_lshl_add_u64 v[90:91], v[88:89], 0, v[6:7]
	flat_store_dwordx4 v[90:91], v[10:13]
	ds_read_b32 v6, v67 offset:64
	ds_read_b32 v10, v67 offset:196
	ds_read_b32 v11, v67 offset:328
	ds_read_b32 v12, v67 offset:460
	ds_read_b32 v13, v67 offset:592
	ds_read_b32 v90, v67 offset:724
	ds_read_b32 v91, v67 offset:856
	ds_read_b32 v92, v67 offset:988
	s_waitcnt lgkmcnt(0)
	v_cvt_pk_bf16_f32 v10, v6, v10
	v_or_b32_e32 v6, s12, v82
	v_lshlrev_b32_e32 v6, 11, v6
	v_cvt_pk_bf16_f32 v11, v11, v12
	v_cvt_pk_bf16_f32 v12, v13, v90
	v_cvt_pk_bf16_f32 v13, v91, v92
	v_lshl_add_u64 v[90:91], v[88:89], 0, v[6:7]
	flat_store_dwordx4 v[90:91], v[10:13]
	ds_read_b32 v6, v67 offset:96
	ds_read_b32 v10, v67 offset:228
	ds_read_b32 v11, v67 offset:360
	ds_read_b32 v12, v67 offset:492
	ds_read_b32 v13, v67 offset:624
	ds_read_b32 v90, v67 offset:756
	ds_read_b32 v91, v67 offset:888
	ds_read_b32 v92, v67 offset:1020
	s_waitcnt lgkmcnt(0)
	v_cvt_pk_bf16_f32 v10, v6, v10
	v_or_b32_e32 v6, s12, v83
	v_lshlrev_b32_e32 v6, 11, v6
	v_cvt_pk_bf16_f32 v11, v11, v12
	v_cvt_pk_bf16_f32 v12, v13, v90
	v_cvt_pk_bf16_f32 v13, v91, v92
	v_lshl_add_u64 v[88:89], v[88:89], 0, v[6:7]
	flat_store_dwordx4 v[88:89], v[10:13]
	s_waitcnt lgkmcnt(0)

; __device__ __forceinline__ void transpose_item(const float* W, int K, int N, bf16_t* WT, int n0d, int n0s, float scale, int k0, float* scr, int lane, bool gperm = false, const float* kgain = nullptr) {
;     ...
;     } else if (n0s >= 0) {
; #pragma unroll
;         for (int i = 0; i < 32; ++i) { const int kk = 2 * i + (lane >> 5); scr[kk * 33 + (lane & 31)] = W[(size_t)(k0 + kk) * N + n0s + (lane & 31)] * (kgain ? scale * kgain[k0 + kk] : scale); }
;     } else {
; #pragma unroll
;         for (int i = 0; i < 32; ++i) { const int kk = 2 * i + (lane >> 5); scr[kk * 33 + (lane & 31)] = 0.f; }
;     }
;     __builtin_amdgcn_wave_barrier(); asm volatile("s_waitcnt lgkmcnt(0)" ::: "memory");
; __device__ __forceinline__ void prologue(const Args& a, unsigned char* ws, char* lds, int gw, int NGW, int wave, int lane) {
;     ...
;         if (r < I_IN) { const int nb = r % (NPROJ / 32), kb = r / (NPROJ / 32); const int n0d = nb * 32; int n0s; float sc = 1.f;
;             if (n0d < PD) { n0s = n0d; if (n0d < 256) sc = 0.17677669529663687f * LOG2E; else if (n0d >= PB && n0d < PB + 256) sc = 0.125f * LOG2E; }
;             else if (n0d < PC) n0s = n0d - PD + 1888;
;             else if (n0d < PC + 352) n0s = n0d - PC + 1536;
;             else if (n0d < PG) n0s = -1;
;             else n0s = n0d - PG + 2400;
;             transpose_item(a.in[3] + (size_t)l * DM * 6496, DM, 6496, (bf16_t*)(ws + WS_WIN) + (size_t)l * NPROJ * DM, n0d, n0s, sc, kb * 64, scr, lane, n0d >= PG, a.in[2] + l * DM); continue; }
.LBB0_113:
	v_mov_b32_e32 v6, 0
	s_andn2_b64 vcc, exec, s[0:1]
	v_mov_b32_e32 v10, v69
	s_cbranch_vccnz .LBB0_179
	s_lshl_b64 s[0:1], s[12:13], 2
	s_add_u32 s0, s20, s0
	s_addc_u32 s1, s21, s1
	v_lshlrev_b32_e32 v6, 2, v4
	v_lshl_add_u64 v[10:11], s[0:1], 0, v[6:7]
	v_or_b32_e32 v12, s16, v2
	v_mul_hi_i32_i24_e32 v91, 0x6580, v12
	v_mul_i32_i24_e32 v90, 0x6580, v12
	v_lshl_add_u64 v[90:91], v[10:11], 0, v[90:91]
	global_load_dword v126, v[90:91], off
	v_or_b32_e32 v12, s16, v14
	v_mul_hi_i32_i24_e32 v91, 0x6580, v12
	v_mul_i32_i24_e32 v90, 0x6580, v12
	v_lshl_add_u64 v[90:91], v[10:11], 0, v[90:91]
	global_load_dword v127, v[90:91], off
	v_or_b32_e32 v12, s16, v16
	v_mul_hi_i32_i24_e32 v91, 0x6580, v12
	v_mul_i32_i24_e32 v90, 0x6580, v12
	v_lshl_add_u64 v[90:91], v[10:11], 0, v[90:91]
	global_load_dword v128, v[90:91], off
	v_or_b32_e32 v12, s16, v18
	v_mul_hi_i32_i24_e32 v91, 0x6580, v12
	v_mul_i32_i24_e32 v90, 0x6580, v12
	v_lshl_add_u64 v[90:91], v[10:11], 0, v[90:91]
	global_load_dword v129, v[90:91], off
	v_or_b32_e32 v12, s16, v20
	v_mul_hi_i32_i24_e32 v91, 0x6580, v12
	v_mul_i32_i24_e32 v90, 0x6580, v12
	v_lshl_add_u64 v[90:91], v[10:11], 0, v[90:91]
	global_load_dword v130, v[90:91], off
	v_or_b32_e32 v12, s16, v22
	v_mul_hi_i32_i24_e32 v91, 0x6580, v12
	v_mul_i32_i24_e32 v90, 0x6580, v12
	v_lshl_add_u64 v[90:91], v[10:11], 0, v[90:91]
	global_load_dword v131, v[90:91], off
	v_or_b32_e32 v12, s16, v24
	v_mul_hi_i32_i24_e32 v91, 0x6580, v12
	v_mul_i32_i24_e32 v90, 0x6580, v12
	v_lshl_add_u64 v[90:91], v[10:11], 0, v[90:91]
	global_load_dword v132, v[90:91], off
	v_or_b32_e32 v12, s16, v26
	v_mul_hi_i32_i24_e32 v91, 0x6580, v12
	v_mul_i32_i24_e32 v90, 0x6580, v12
	v_lshl_add_u64 v[90:91], v[10:11], 0, v[90:91]
	global_load_dword v133, v[90:91], off
	v_or_b32_e32 v12, s16, v28
	v_mul_hi_i32_i24_e32 v91, 0x6580, v12
	v_mul_i32_i24_e32 v90, 0x6580, v12
	v_lshl_add_u64 v[90:91], v[10:11], 0, v[90:91]
	global_load_dword v134, v[90:91], off
	v_or_b32_e32 v12, s16, v30
	v_mul_hi_i32_i24_e32 v91, 0x6580, v12
	v_mul_i32_i24_e32 v90, 0x6580, v12
	v_lshl_add_u64 v[90:91], v[10:11], 0, v[90:91]
	global_load_dword v135, v[90:91], off
	v_or_b32_e32 v12, s16, v32
	v_mul_hi_i32_i24_e32 v91, 0x6580, v12
	v_mul_i32_i24_e32 v90, 0x6580, v12
	v_lshl_add_u64 v[90:91], v[10:11], 0, v[90:91]
	global_load_dword v136, v[90:91], off
	v_or_b32_e32 v12, s16, v34
	v_mul_hi_i32_i24_e32 v91, 0x6580, v12
	v_mul_i32_i24_e32 v90, 0x6580, v12
	v_lshl_add_u64 v[90:91], v[10:11], 0, v[90:91]
	global_load_dword v137, v[90:91], off
	v_or_b32_e32 v12, s16, v36
	v_mul_hi_i32_i24_e32 v91, 0x6580, v12
	v_mul_i32_i24_e32 v90, 0x6580, v12
	v_lshl_add_u64 v[90:91], v[10:11], 0, v[90:91]
	global_load_dword v138, v[90:91], off
	v_or_b32_e32 v12, s16, v38
	v_mul_hi_i32_i24_e32 v91, 0x6580, v12
	v_mul_i32_i24_e32 v90, 0x6580, v12
	v_lshl_add_u64 v[90:91], v[10:11], 0, v[90:91]
	global_load_dword v139, v[90:91], off
	v_or_b32_e32 v12, s16, v40
	v_mul_hi_i32_i24_e32 v91, 0x6580, v12
	v_mul_i32_i24_e32 v90, 0x6580, v12
	v_lshl_add_u64 v[90:91], v[10:11], 0, v[90:91]
	global_load_dword v140, v[90:91], off
	v_or_b32_e32 v12, s16, v42
	v_mul_hi_i32_i24_e32 v91, 0x6580, v12
	v_mul_i32_i24_e32 v90, 0x6580, v12
	v_lshl_add_u64 v[90:91], v[10:11], 0, v[90:91]
	global_load_dword v141, v[90:91], off
	v_or_b32_e32 v12, s16, v44
	v_mul_hi_i32_i24_e32 v91, 0x6580, v12
	v_mul_i32_i24_e32 v90, 0x6580, v12
	v_lshl_add_u64 v[90:91], v[10:11], 0, v[90:91]
	global_load_dword v142, v[90:91], off
	v_or_b32_e32 v12, s16, v46
	v_mul_hi_i32_i24_e32 v91, 0x6580, v12
	v_mul_i32_i24_e32 v90, 0x6580, v12
	v_lshl_add_u64 v[90:91], v[10:11], 0, v[90:91]
	global_load_dword v143, v[90:91], off
	v_or_b32_e32 v12, s16, v48
	v_mul_hi_i32_i24_e32 v91, 0x6580, v12
	v_mul_i32_i24_e32 v90, 0x6580, v12
	v_lshl_add_u64 v[90:91], v[10:11], 0, v[90:91]
	global_load_dword v144, v[90:91], off
	v_or_b32_e32 v12, s16, v50
	v_mul_hi_i32_i24_e32 v91, 0x6580, v12
	v_mul_i32_i24_e32 v90, 0x6580, v12
	v_lshl_add_u64 v[90:91], v[10:11], 0, v[90:91]
	global_load_dword v145, v[90:91], off
	v_or_b32_e32 v12, s16, v52
	v_mul_hi_i32_i24_e32 v91, 0x6580, v12
	v_mul_i32_i24_e32 v90, 0x6580, v12
	v_lshl_add_u64 v[90:91], v[10:11], 0, v[90:91]
	global_load_dword v146, v[90:91], off
	v_or_b32_e32 v12, s16, v54
	v_mul_hi_i32_i24_e32 v91, 0x6580, v12
	v_mul_i32_i24_e32 v90, 0x6580, v12
	v_lshl_add_u64 v[90:91], v[10:11], 0, v[90:91]
	global_load_dword v147, v[90:91], off
	v_or_b32_e32 v12, s16, v56
	v_mul_hi_i32_i24_e32 v91, 0x6580, v12
	v_mul_i32_i24_e32 v90, 0x6580, v12
	v_lshl_add_u64 v[90:91], v[10:11], 0, v[90:91]
	global_load_dword v148, v[90:91], off
	v_or_b32_e32 v12, s16, v58
	v_mul_hi_i32_i24_e32 v91, 0x6580, v12
	v_mul_i32_i24_e32 v90, 0x6580, v12
	v_lshl_add_u64 v[90:91], v[10:11], 0, v[90:91]
	global_load_dword v149, v[90:91], off
	v_or_b32_e32 v12, s16, v60
	v_mul_hi_i32_i24_e32 v91, 0x6580, v12
	v_mul_i32_i24_e32 v90, 0x6580, v12
	v_lshl_add_u64 v[90:91], v[10:11], 0, v[90:91]
	global_load_dword v150, v[90:91], off
	v_or_b32_e32 v12, s16, v62
	v_mul_hi_i32_i24_e32 v91, 0x6580, v12
	v_mul_i32_i24_e32 v90, 0x6580, v12
	v_lshl_add_u64 v[90:91], v[10:11], 0, v[90:91]
	global_load_dword v151, v[90:91], off
	v_or_b32_e32 v12, s16, v64
	v_mul_hi_i32_i24_e32 v91, 0x6580, v12
	v_mul_i32_i24_e32 v90, 0x6580, v12
	v_lshl_add_u64 v[90:91], v[10:11], 0, v[90:91]
	global_load_dword v152, v[90:91], off
	v_or_b32_e32 v12, s16, v71
	v_mul_hi_i32_i24_e32 v91, 0x6580, v12
	v_mul_i32_i24_e32 v90, 0x6580, v12
	v_lshl_add_u64 v[90:91], v[10:11], 0, v[90:91]
	global_load_dword v153, v[90:91], off
	v_or_b32_e32 v12, s16, v73
	v_mul_hi_i32_i24_e32 v91, 0x6580, v12
; __device__ __forceinline__ void transpose_item(const float* W, int K, int N, bf16_t* WT, int n0d, int n0s, float scale, int k0, float* scr, int lane, bool gperm = false, const float* kgain = nullptr) {
;     ...
;     } else if (n0s >= 0) {
; #pragma unroll
;         for (int i = 0; i < 32; ++i) { const int kk = 2 * i + (lane >> 5); scr[kk * 33 + (lane & 31)] = W[(size_t)(k0 + kk) * N + n0s + (lane & 31)] * (kgain ? scale * kgain[k0 + kk] : scale); }
;     } else {
; #pragma unroll
;         for (int i = 0; i < 32; ++i) { const int kk = 2 * i + (lane >> 5); scr[kk * 33 + (lane & 31)] = 0.f; }
;     }
;     __builtin_amdgcn_wave_barrier(); asm volatile("s_waitcnt lgkmcnt(0)" ::: "memory");
	v_mul_i32_i24_e32 v90, 0x6580, v12
	v_lshl_add_u64 v[90:91], v[10:11], 0, v[90:91]
	global_load_dword v154, v[90:91], off
	v_or_b32_e32 v12, s16, v75
	v_mul_hi_i32_i24_e32 v91, 0x6580, v12
	v_mul_i32_i24_e32 v90, 0x6580, v12
	v_lshl_add_u64 v[90:91], v[10:11], 0, v[90:91]
	global_load_dword v155, v[90:91], off
	v_or_b32_e32 v12, s16, v77
	v_mul_hi_i32_i24_e32 v91, 0x6580, v12
	v_mul_i32_i24_e32 v90, 0x6580, v12
	v_lshl_add_u64 v[90:91], v[10:11], 0, v[90:91]
	global_load_dword v156, v[90:91], off
	v_or_b32_e32 v12, s16, v79
	v_mul_hi_i32_i24_e32 v91, 0x6580, v12
	v_mul_i32_i24_e32 v90, 0x6580, v12
	v_lshl_add_u64 v[90:91], v[10:11], 0, v[90:91]
	global_load_dword v157, v[90:91], off
	v_cndmask_b32_e64 v13, 0, 1, s[10:11]
	v_cmp_ne_u32_e64 s[0:1], 1, v13
	v_mov_b32_e32 v194, 1.0
	v_mov_b32_e32 v195, 1.0
	v_mov_b32_e32 v196, 1.0
	v_mov_b32_e32 v197, 1.0
	v_mov_b32_e32 v198, 1.0
	v_mov_b32_e32 v199, 1.0
	v_mov_b32_e32 v200, 1.0
	v_mov_b32_e32 v201, 1.0
	v_mov_b32_e32 v202, 1.0
	v_mov_b32_e32 v203, 1.0
	v_mov_b32_e32 v204, 1.0
	v_mov_b32_e32 v205, 1.0
	v_mov_b32_e32 v206, 1.0
	v_mov_b32_e32 v207, 1.0
	v_mov_b32_e32 v208, 1.0
	v_mov_b32_e32 v209, 1.0
	v_mov_b32_e32 v210, 1.0
	v_mov_b32_e32 v211, 1.0
	v_mov_b32_e32 v212, 1.0
	v_mov_b32_e32 v213, 1.0
	v_mov_b32_e32 v214, 1.0
	v_mov_b32_e32 v215, 1.0
	v_mov_b32_e32 v216, 1.0
	v_mov_b32_e32 v217, 1.0
	v_mov_b32_e32 v218, 1.0
	v_mov_b32_e32 v219, 1.0
	v_mov_b32_e32 v220, 1.0
	v_mov_b32_e32 v221, 1.0
	v_mov_b32_e32 v222, 1.0
	v_mov_b32_e32 v223, 1.0
	v_mov_b32_e32 v224, 1.0
	v_mov_b32_e32 v225, 1.0
	s_and_b64 vcc, exec, s[0:1]
	s_cbranch_vccnz .Lpro2_nokg
	s_ashr_i32 s17, s16, 31
	v_lshl_add_u64 v[90:91], s[16:17], 0, v[2:3]
	v_lshl_add_u64 v[90:91], v[90:91], 2, s[18:19]
	global_load_dword v194, v[90:91], off
	global_load_dword v195, v[90:91], off offset:8
	global_load_dword v196, v[90:91], off offset:16
	global_load_dword v197, v[90:91], off offset:24
	global_load_dword v198, v[90:91], off offset:32
	global_load_dword v199, v[90:91], off offset:40
	global_load_dword v200, v[90:91], off offset:48
	global_load_dword v201, v[90:91], off offset:56
	global_load_dword v202, v[90:91], off offset:64
	global_load_dword v203, v[90:91], off offset:72
	global_load_dword v204, v[90:91], off offset:80
	global_load_dword v205, v[90:91], off offset:88
	global_load_dword v206, v[90:91], off offset:96
	global_load_dword v207, v[90:91], off offset:104
	global_load_dword v208, v[90:91], off offset:112
	global_load_dword v209, v[90:91], off offset:120
	global_load_dword v210, v[90:91], off offset:128
	global_load_dword v211, v[90:91], off offset:136
	global_load_dword v212, v[90:91], off offset:144
	global_load_dword v213, v[90:91], off offset:152
	global_load_dword v214, v[90:91], off offset:160
	global_load_dword v215, v[90:91], off offset:168
	global_load_dword v216, v[90:91], off offset:176
	global_load_dword v217, v[90:91], off offset:184
	global_load_dword v218, v[90:91], off offset:192
	global_load_dword v219, v[90:91], off offset:200
	global_load_dword v220, v[90:91], off offset:208
	global_load_dword v221, v[90:91], off offset:216
	global_load_dword v222, v[90:91], off offset:224
	global_load_dword v223, v[90:91], off offset:232
	global_load_dword v224, v[90:91], off offset:240
	global_load_dword v225, v[90:91], off offset:248
.Lpro2_nokg:
	s_waitcnt vmcnt(0)
	v_mul_f32_e32 v194, v88, v194
	v_mul_f32_e32 v126, v126, v194
	ds_write_b32 v9, v126
	v_mul_f32_e32 v195, v88, v195
	v_mul_f32_e32 v127, v127, v195
	ds_write_b32 v15, v127
	v_mul_f32_e32 v196, v88, v196
	v_mul_f32_e32 v128, v128, v196
	ds_write_b32 v17, v128
	v_mul_f32_e32 v197, v88, v197
	v_mul_f32_e32 v129, v129, v197
	ds_write_b32 v19, v129
	v_mul_f32_e32 v198, v88, v198
	v_mul_f32_e32 v130, v130, v198
	ds_write_b32 v21, v130
	v_mul_f32_e32 v199, v88, v199
	v_mul_f32_e32 v131, v131, v199
	ds_write_b32 v23, v131
	v_mul_f32_e32 v200, v88, v200
	v_mul_f32_e32 v132, v132, v200
	ds_write_b32 v25, v132
	v_mul_f32_e32 v201, v88, v201
	v_mul_f32_e32 v133, v133, v201
	ds_write_b32 v27, v133
	v_mul_f32_e32 v202, v88, v202
	v_mul_f32_e32 v134, v134, v202
	ds_write_b32 v29, v134
	v_mul_f32_e32 v203, v88, v203
	v_mul_f32_e32 v135, v135, v203
	ds_write_b32 v31, v135
	v_mul_f32_e32 v204, v88, v204
	v_mul_f32_e32 v136, v136, v204
	ds_write_b32 v33, v136
	v_mul_f32_e32 v205, v88, v205
	v_mul_f32_e32 v137, v137, v205
	ds_write_b32 v35, v137
	v_mul_f32_e32 v206, v88, v206
	v_mul_f32_e32 v138, v138, v206
	ds_write_b32 v37, v138
	v_mul_f32_e32 v207, v88, v207
	v_mul_f32_e32 v139, v139, v207
	ds_write_b32 v39, v139
	v_mul_f32_e32 v208, v88, v208
	v_mul_f32_e32 v140, v140, v208
	ds_write_b32 v41, v140
	v_mul_f32_e32 v209, v88, v209
	v_mul_f32_e32 v141, v141, v209
	ds_write_b32 v43, v141
	v_mul_f32_e32 v210, v88, v210
	v_mul_f32_e32 v142, v142, v210
	ds_write_b32 v45, v142
	v_mul_f32_e32 v211, v88, v211
	v_mul_f32_e32 v143, v143, v211
	ds_write_b32 v47, v143
	v_mul_f32_e32 v212, v88, v212
	v_mul_f32_e32 v144, v144, v212
	ds_write_b32 v49, v144
	v_mul_f32_e32 v213, v88, v213
	v_mul_f32_e32 v145, v145, v213
	ds_write_b32 v51, v145
	v_mul_f32_e32 v214, v88, v214
	v_mul_f32_e32 v146, v146, v214
	ds_write_b32 v53, v146
	v_mul_f32_e32 v215, v88, v215
	v_mul_f32_e32 v147, v147, v215
	ds_write_b32 v55, v147
	v_mul_f32_e32 v216, v88, v216
	v_mul_f32_e32 v148, v148, v216
	ds_write_b32 v57, v148
	v_mul_f32_e32 v217, v88, v217
	v_mul_f32_e32 v149, v149, v217
	ds_write_b32 v59, v149
	v_mul_f32_e32 v218, v88, v218
	v_mul_f32_e32 v150, v150, v218
	ds_write_b32 v61, v150
	v_mul_f32_e32 v219, v88, v219
	v_mul_f32_e32 v151, v151, v219
	ds_write_b32 v63, v151
	v_mul_f32_e32 v220, v88, v220
	v_mul_f32_e32 v152, v152, v220
	ds_write_b32 v65, v152
	v_mul_f32_e32 v221, v88, v221
	v_mul_f32_e32 v153, v153, v221
	ds_write_b32 v72, v153
	v_mul_f32_e32 v222, v88, v222
	v_mul_f32_e32 v154, v154, v222
	ds_write_b32 v74, v154
	v_mul_f32_e32 v223, v88, v223
	v_mul_f32_e32 v155, v155, v223
	ds_write_b32 v76, v155
	v_mul_f32_e32 v224, v88, v224
	v_mul_f32_e32 v156, v156, v224
	ds_write_b32 v78, v156
	v_mul_f32_e32 v225, v88, v225
	v_mul_f32_e32 v6, v157, v225
	v_mov_b32_e32 v10, v84

; __device__ __forceinline__ void transpose_item(const float* W, int K, int N, bf16_t* WT, int n0d, int n0s, float scale, int k0, float* scr, int lane, bool gperm = false, const float* kgain = nullptr) {
;     if (gperm) {
;         const int cg = n0d - PG + (lane & 31), tg = cg >> 8, cc = cg & 255, gi = 2 * (cc >> 7) + ((cc >> 2) & 1), ch = tg * 64 + 16 * ((cc >> 5) & 3) + 4 * ((cc >> 3) & 3) + (cc & 3);
;         const int src = 2400 + gi * 1024 + ch;
; #pragma unroll
;         for (int i = 0; i < 32; ++i) { const int kk = 2 * i + (lane >> 5); scr[kk * 33 + (lane & 31)] = W[(size_t)(k0 + kk) * N + src] * kgain[k0 + kk]; }
; __device__ __forceinline__ void prologue(const Args& a, unsigned char* ws, char* lds, int gw, int NGW, int wave, int lane) {
;     ...
;         if (r < I_IN) { const int nb = r % (NPROJ / 32), kb = r / (NPROJ / 32); const int n0d = nb * 32; int n0s; float sc = 1.f;
;             if (n0d < PD) { n0s = n0d; if (n0d < 256) sc = 0.17677669529663687f * LOG2E; else if (n0d >= PB && n0d < PB + 256) sc = 0.125f * LOG2E; }
;             else if (n0d < PC) n0s = n0d - PD + 1888;
;             else if (n0d < PC + 352) n0s = n0d - PC + 1536;
;             else if (n0d < PG) n0s = -1;
;             else n0s = n0d - PG + 2400;
;             transpose_item(a.in[3] + (size_t)l * DM * 6496, DM, 6496, (bf16_t*)(ws + WS_WIN) + (size_t)l * NPROJ * DM, n0d, n0s, sc, kb * 64, scr, lane, n0d >= PG, a.in[2] + l * DM); continue; }
.LBB0_180:
	s_andn2_b64 vcc, exec, s[0:1]
	s_cbranch_vccnz .LBB0_9
	s_add_i32 s0, s15, 0xfffff600
	v_or_b32_e32 v6, s15, v4
	s_lshr_b32 s1, s15, 6
	s_ashr_i32 s0, s0, 2
	v_and_or_b32 v10, s1, 2, v85
	s_andn2_b32 s0, s0, 63
	v_lshrrev_b32_e32 v6, 1, v6
	v_and_b32_e32 v6, 60, v6
	v_lshlrev_b32_e32 v10, 10, v10
	v_add_u32_e32 v11, s0, v70
	v_add3_u32 v6, v11, v6, v10
	v_lshl_add_u64 v[12:13], v[6:7], 2, s[20:21]
	v_or_b32_e32 v10, s16, v2
	v_mul_hi_i32_i24_e32 v89, 0x6580, v10
	v_mul_i32_i24_e32 v88, 0x6580, v10
	v_lshl_add_u64 v[88:89], v[12:13], 0, v[88:89]
	global_load_dword v126, v[88:89], off
	v_or_b32_e32 v10, s16, v14
	v_mul_hi_i32_i24_e32 v89, 0x6580, v10
	v_mul_i32_i24_e32 v88, 0x6580, v10
	v_lshl_add_u64 v[88:89], v[12:13], 0, v[88:89]
	global_load_dword v127, v[88:89], off
	v_or_b32_e32 v10, s16, v16
	v_mul_hi_i32_i24_e32 v89, 0x6580, v10
	v_mul_i32_i24_e32 v88, 0x6580, v10
	v_lshl_add_u64 v[88:89], v[12:13], 0, v[88:89]
	global_load_dword v128, v[88:89], off
	v_or_b32_e32 v10, s16, v18
	v_mul_hi_i32_i24_e32 v89, 0x6580, v10
	v_mul_i32_i24_e32 v88, 0x6580, v10
	v_lshl_add_u64 v[88:89], v[12:13], 0, v[88:89]
	global_load_dword v129, v[88:89], off
	v_or_b32_e32 v10, s16, v20
	v_mul_hi_i32_i24_e32 v89, 0x6580, v10
	v_mul_i32_i24_e32 v88, 0x6580, v10
	v_lshl_add_u64 v[88:89], v[12:13], 0, v[88:89]
	global_load_dword v130, v[88:89], off
	v_or_b32_e32 v10, s16, v22
	v_mul_hi_i32_i24_e32 v89, 0x6580, v10
	v_mul_i32_i24_e32 v88, 0x6580, v10
	v_lshl_add_u64 v[88:89], v[12:13], 0, v[88:89]
	global_load_dword v131, v[88:89], off
	v_or_b32_e32 v10, s16, v24
	v_mul_hi_i32_i24_e32 v89, 0x6580, v10
	v_mul_i32_i24_e32 v88, 0x6580, v10
	v_lshl_add_u64 v[88:89], v[12:13], 0, v[88:89]
	global_load_dword v132, v[88:89], off
	v_or_b32_e32 v10, s16, v26
	v_mul_hi_i32_i24_e32 v89, 0x6580, v10
	v_mul_i32_i24_e32 v88, 0x6580, v10
	v_lshl_add_u64 v[88:89], v[12:13], 0, v[88:89]
	global_load_dword v133, v[88:89], off
	v_or_b32_e32 v10, s16, v28
	v_mul_hi_i32_i24_e32 v89, 0x6580, v10
	v_mul_i32_i24_e32 v88, 0x6580, v10
	v_lshl_add_u64 v[88:89], v[12:13], 0, v[88:89]
	global_load_dword v134, v[88:89], off
	v_or_b32_e32 v10, s16, v30
	v_mul_hi_i32_i24_e32 v89, 0x6580, v10
	v_mul_i32_i24_e32 v88, 0x6580, v10
	v_lshl_add_u64 v[88:89], v[12:13], 0, v[88:89]
	global_load_dword v135, v[88:89], off
	v_or_b32_e32 v10, s16, v32
	v_mul_hi_i32_i24_e32 v89, 0x6580, v10
	v_mul_i32_i24_e32 v88, 0x6580, v10
	v_lshl_add_u64 v[88:89], v[12:13], 0, v[88:89]
	global_load_dword v136, v[88:89], off
	v_or_b32_e32 v10, s16, v34
	v_mul_hi_i32_i24_e32 v89, 0x6580, v10
	v_mul_i32_i24_e32 v88, 0x6580, v10
	v_lshl_add_u64 v[88:89], v[12:13], 0, v[88:89]
	global_load_dword v137, v[88:89], off
	v_or_b32_e32 v10, s16, v36
	v_mul_hi_i32_i24_e32 v89, 0x6580, v10
	v_mul_i32_i24_e32 v88, 0x6580, v10
	v_lshl_add_u64 v[88:89], v[12:13], 0, v[88:89]
	global_load_dword v138, v[88:89], off
	v_or_b32_e32 v10, s16, v38
	v_mul_hi_i32_i24_e32 v89, 0x6580, v10
	v_mul_i32_i24_e32 v88, 0x6580, v10
	v_lshl_add_u64 v[88:89], v[12:13], 0, v[88:89]
	global_load_dword v139, v[88:89], off
	v_or_b32_e32 v10, s16, v40
	v_mul_hi_i32_i24_e32 v89, 0x6580, v10
	v_mul_i32_i24_e32 v88, 0x6580, v10
	v_lshl_add_u64 v[88:89], v[12:13], 0, v[88:89]
	global_load_dword v140, v[88:89], off
	v_or_b32_e32 v10, s16, v42
	v_mul_hi_i32_i24_e32 v89, 0x6580, v10
	v_mul_i32_i24_e32 v88, 0x6580, v10
	v_lshl_add_u64 v[88:89], v[12:13], 0, v[88:89]
	global_load_dword v141, v[88:89], off
	v_or_b32_e32 v10, s16, v44
	v_mul_hi_i32_i24_e32 v89, 0x6580, v10
	v_mul_i32_i24_e32 v88, 0x6580, v10
	v_lshl_add_u64 v[88:89], v[12:13], 0, v[88:89]
	global_load_dword v142, v[88:89], off
	v_or_b32_e32 v10, s16, v46
	v_mul_hi_i32_i24_e32 v89, 0x6580, v10
	v_mul_i32_i24_e32 v88, 0x6580, v10
	v_lshl_add_u64 v[88:89], v[12:13], 0, v[88:89]
	global_load_dword v143, v[88:89], off
	v_or_b32_e32 v10, s16, v48
	v_mul_hi_i32_i24_e32 v89, 0x6580, v10
	v_mul_i32_i24_e32 v88, 0x6580, v10
	v_lshl_add_u64 v[88:89], v[12:13], 0, v[88:89]
	global_load_dword v144, v[88:89], off
	v_or_b32_e32 v10, s16, v50
	v_mul_hi_i32_i24_e32 v89, 0x6580, v10
	v_mul_i32_i24_e32 v88, 0x6580, v10
	v_lshl_add_u64 v[88:89], v[12:13], 0, v[88:89]
	global_load_dword v145, v[88:89], off
	v_or_b32_e32 v10, s16, v52
	v_mul_hi_i32_i24_e32 v89, 0x6580, v10
	v_mul_i32_i24_e32 v88, 0x6580, v10
	v_lshl_add_u64 v[88:89], v[12:13], 0, v[88:89]
	global_load_dword v146, v[88:89], off
	v_or_b32_e32 v10, s16, v54
	v_mul_hi_i32_i24_e32 v89, 0x6580, v10
	v_mul_i32_i24_e32 v88, 0x6580, v10
	v_lshl_add_u64 v[88:89], v[12:13], 0, v[88:89]
	global_load_dword v147, v[88:89], off
	v_or_b32_e32 v10, s16, v56
	v_mul_hi_i32_i24_e32 v89, 0x6580, v10
	v_mul_i32_i24_e32 v88, 0x6580, v10
	v_lshl_add_u64 v[88:89], v[12:13], 0, v[88:89]
	global_load_dword v148, v[88:89], off
	v_or_b32_e32 v10, s16, v58
	v_mul_hi_i32_i24_e32 v89, 0x6580, v10
	v_mul_i32_i24_e32 v88, 0x6580, v10
	v_lshl_add_u64 v[88:89], v[12:13], 0, v[88:89]
	global_load_dword v149, v[88:89], off
	v_or_b32_e32 v10, s16, v60
; __device__ __forceinline__ void transpose_item(const float* W, int K, int N, bf16_t* WT, int n0d, int n0s, float scale, int k0, float* scr, int lane, bool gperm = false, const float* kgain = nullptr) {
;     if (gperm) {
;         const int cg = n0d - PG + (lane & 31), tg = cg >> 8, cc = cg & 255, gi = 2 * (cc >> 7) + ((cc >> 2) & 1), ch = tg * 64 + 16 * ((cc >> 5) & 3) + 4 * ((cc >> 3) & 3) + (cc & 3);
;         const int src = 2400 + gi * 1024 + ch;
; #pragma unroll
;         for (int i = 0; i < 32; ++i) { const int kk = 2 * i + (lane >> 5); scr[kk * 33 + (lane & 31)] = W[(size_t)(k0 + kk) * N + src] * kgain[k0 + kk]; }
;     } else if (n0s >= 0) {
; #pragma unroll
;         for (int i = 0; i < 32; ++i) { const int kk = 2 * i + (lane >> 5); scr[kk * 33 + (lane & 31)] = W[(size_t)(k0 + kk) * N + n0s + (lane & 31)] * (kgain ? scale * kgain[k0 + kk] : scale); }
;     } else {
; #pragma unroll
;         for (int i = 0; i < 32; ++i) { const int kk = 2 * i + (lane >> 5); scr[kk * 33 + (lane & 31)] = 0.f; }
;     }
;     __builtin_amdgcn_wave_barrier(); asm volatile("s_waitcnt lgkmcnt(0)" ::: "memory");
	v_mul_hi_i32_i24_e32 v89, 0x6580, v10
	v_mul_i32_i24_e32 v88, 0x6580, v10
	v_lshl_add_u64 v[88:89], v[12:13], 0, v[88:89]
	global_load_dword v150, v[88:89], off
	v_or_b32_e32 v10, s16, v62
	v_mul_hi_i32_i24_e32 v89, 0x6580, v10
	v_mul_i32_i24_e32 v88, 0x6580, v10
	v_lshl_add_u64 v[88:89], v[12:13], 0, v[88:89]
	global_load_dword v151, v[88:89], off
	v_or_b32_e32 v10, s16, v64
	v_mul_hi_i32_i24_e32 v89, 0x6580, v10
	v_mul_i32_i24_e32 v88, 0x6580, v10
	v_lshl_add_u64 v[88:89], v[12:13], 0, v[88:89]
	global_load_dword v152, v[88:89], off
	v_or_b32_e32 v10, s16, v71
	v_mul_hi_i32_i24_e32 v89, 0x6580, v10
	v_mul_i32_i24_e32 v88, 0x6580, v10
	v_lshl_add_u64 v[88:89], v[12:13], 0, v[88:89]
	global_load_dword v153, v[88:89], off
	v_or_b32_e32 v10, s16, v73
	v_mul_hi_i32_i24_e32 v89, 0x6580, v10
	v_mul_i32_i24_e32 v88, 0x6580, v10
	v_lshl_add_u64 v[88:89], v[12:13], 0, v[88:89]
	global_load_dword v154, v[88:89], off
	v_or_b32_e32 v10, s16, v75
	v_mul_hi_i32_i24_e32 v89, 0x6580, v10
	v_mul_i32_i24_e32 v88, 0x6580, v10
	v_lshl_add_u64 v[88:89], v[12:13], 0, v[88:89]
	global_load_dword v155, v[88:89], off
	v_or_b32_e32 v10, s16, v77
	v_mul_hi_i32_i24_e32 v89, 0x6580, v10
	v_mul_i32_i24_e32 v88, 0x6580, v10
	v_lshl_add_u64 v[88:89], v[12:13], 0, v[88:89]
	global_load_dword v156, v[88:89], off
	v_or_b32_e32 v10, s16, v79
	v_mul_hi_i32_i24_e32 v89, 0x6580, v10
	v_mul_i32_i24_e32 v88, 0x6580, v10
	v_lshl_add_u64 v[88:89], v[12:13], 0, v[88:89]
	global_load_dword v157, v[88:89], off
	s_ashr_i32 s17, s16, 31
	v_lshl_add_u64 v[10:11], s[16:17], 0, v[2:3]
	v_lshl_add_u64 v[10:11], v[10:11], 2, s[18:19]
	global_load_dword v194, v[10:11], off
	global_load_dword v195, v[10:11], off offset:8
	global_load_dword v196, v[10:11], off offset:16
	global_load_dword v197, v[10:11], off offset:24
	global_load_dword v198, v[10:11], off offset:32
	global_load_dword v199, v[10:11], off offset:40
	global_load_dword v200, v[10:11], off offset:48
	global_load_dword v201, v[10:11], off offset:56
	global_load_dword v202, v[10:11], off offset:64
	global_load_dword v203, v[10:11], off offset:72
	global_load_dword v204, v[10:11], off offset:80
	global_load_dword v205, v[10:11], off offset:88
	global_load_dword v206, v[10:11], off offset:96
	global_load_dword v207, v[10:11], off offset:104
	global_load_dword v208, v[10:11], off offset:112
	global_load_dword v209, v[10:11], off offset:120
	global_load_dword v210, v[10:11], off offset:128
	global_load_dword v211, v[10:11], off offset:136
	global_load_dword v212, v[10:11], off offset:144
	global_load_dword v213, v[10:11], off offset:152
	global_load_dword v214, v[10:11], off offset:160
	global_load_dword v215, v[10:11], off offset:168
	global_load_dword v216, v[10:11], off offset:176
	global_load_dword v217, v[10:11], off offset:184
	global_load_dword v218, v[10:11], off offset:192
	global_load_dword v219, v[10:11], off offset:200
	global_load_dword v220, v[10:11], off offset:208
	global_load_dword v221, v[10:11], off offset:216
	global_load_dword v222, v[10:11], off offset:224
	global_load_dword v223, v[10:11], off offset:232
	global_load_dword v224, v[10:11], off offset:240
	global_load_dword v225, v[10:11], off offset:248
	s_waitcnt vmcnt(0)
	v_mul_f32_e32 v126, v126, v194
	ds_write_b32 v9, v126
	v_mul_f32_e32 v127, v127, v195
	ds_write_b32 v15, v127
	v_mul_f32_e32 v128, v128, v196
	ds_write_b32 v17, v128
	v_mul_f32_e32 v129, v129, v197
	ds_write_b32 v19, v129
	v_mul_f32_e32 v130, v130, v198
	ds_write_b32 v21, v130
	v_mul_f32_e32 v131, v131, v199
	ds_write_b32 v23, v131
	v_mul_f32_e32 v132, v132, v200
	ds_write_b32 v25, v132
	v_mul_f32_e32 v133, v133, v201
	ds_write_b32 v27, v133
	v_mul_f32_e32 v134, v134, v202
	ds_write_b32 v29, v134
	v_mul_f32_e32 v135, v135, v203
	ds_write_b32 v31, v135
	v_mul_f32_e32 v136, v136, v204
	ds_write_b32 v33, v136
	v_mul_f32_e32 v137, v137, v205
	ds_write_b32 v35, v137
	v_mul_f32_e32 v138, v138, v206
	ds_write_b32 v37, v138
	v_mul_f32_e32 v139, v139, v207
	ds_write_b32 v39, v139
	v_mul_f32_e32 v140, v140, v208
	ds_write_b32 v41, v140
	v_mul_f32_e32 v141, v141, v209
	ds_write_b32 v43, v141
	v_mul_f32_e32 v142, v142, v210
	ds_write_b32 v45, v142
	v_mul_f32_e32 v143, v143, v211
	ds_write_b32 v47, v143
	v_mul_f32_e32 v144, v144, v212
	ds_write_b32 v49, v144
	v_mul_f32_e32 v145, v145, v213
	ds_write_b32 v51, v145
	v_mul_f32_e32 v146, v146, v214
	ds_write_b32 v53, v146
	v_mul_f32_e32 v147, v147, v215
	ds_write_b32 v55, v147
	v_mul_f32_e32 v148, v148, v216
	ds_write_b32 v57, v148
	v_mul_f32_e32 v149, v149, v217
	ds_write_b32 v59, v149
	v_mul_f32_e32 v150, v150, v218
	ds_write_b32 v61, v150
	v_mul_f32_e32 v151, v151, v219
	ds_write_b32 v63, v151
	v_mul_f32_e32 v152, v152, v220
	ds_write_b32 v65, v152
	v_mul_f32_e32 v153, v153, v221
	ds_write_b32 v72, v153
	v_mul_f32_e32 v154, v154, v222
	ds_write_b32 v74, v154
	v_mul_f32_e32 v155, v155, v223
	ds_write_b32 v76, v155
	v_mul_f32_e32 v156, v156, v224
	ds_write_b32 v78, v156
	v_mul_f32_e32 v6, v157, v225
	v_mov_b32_e32 v10, v84
	s_branch .LBB0_9

; #define PH(k) _Pragma("unroll 1") for (int rep_ = 0; rep_ < (int)(((PH_MASK >> (k)) & 1) + ((DUP_MASK >> (k)) & 1)); ++rep_)
; #define TIDS() const int tid = otid(), lane = tid & 63, wave = __builtin_amdgcn_readfirstlane(tid >> 6), gw = vcu * NWAVES + wave, gtid = vcu * NTHR + tid; (void)lane; (void)gw; (void)gtid
; #define WSP(name) unsigned char* name = a.ws; asm volatile("" : "+s"(name))
; #define GSYNC() xcd_barrier(bar)
; __global__ void __launch_bounds__(NTHR, 2) mega_fwd(Args a) {
;     ...
; #pragma unroll 1
;         for (int l = 0; l < DEPTH; ++l) {
;             int row_g0 = g * TMAX, T = (g < 2) ? TMAX : (NTOK - 2 * TMAX); asm volatile("" : "+s"(row_g0), "+s"(T));
;             if (l == 0) {
;     ...
;             PH(11) { WSP(w); TIDS(); if (l == DEPTH - 1) final_norm_phase(a.out, row_g0, T, (const bf16_t*)(w + WS_XN), (const float*)(w + WS_MRG), a.in[23], gw, NGW, lane); }
;             if (l == DEPTH - 1) GSYNC();
.LBB0_197:
	s_lshl_b32 s0, s5, 15
	v_writelane_b32 v254, s0, 58
	s_cmp_eq_u32 s5, 2
	s_movk_i32 s0, 0x4000
	v_writelane_b32 v254, s5, 59
	s_cselect_b32 s0, s0, 0x8000
	v_writelane_b32 v254, s0, 60
	s_mov_b64 s[0:1], 0
	v_writelane_b32 v254, s0, 61
	s_mov_b64 s[36:37], -1
	s_mov_b32 s62, s17
	v_writelane_b32 v254, s1, 62
	s_branch .LBB0_201
.LBB0_200:
	s_mov_b64 s[0:1], -1
	v_writelane_b32 v254, s0, 61
	s_mov_b32 s62, 1
	s_mov_b64 s[36:37], 0
	v_writelane_b32 v254, s1, 62
	s_nop 0
	v_readlane_b32 s0, v254, 63
	v_readlane_b32 s1, v255, 0
	s_and_b64 vcc, exec, s[0:1]
	s_cbranch_vccnz .LBB0_196

; #define TIDS() const int tid = otid(), lane = tid & 63, wave = __builtin_amdgcn_readfirstlane(tid >> 6), gw = vcu * NWAVES + wave, gtid = vcu * NTHR + tid; (void)lane; (void)gw; (void)gtid
; #define WSP(name) unsigned char* name = a.ws; asm volatile("" : "+s"(name))
; __global__ void __launch_bounds__(NTHR, 2) mega_fwd(Args a) {
;     ...
;                 for (int hh = 0; hh < 4; ++hh) { WSP(w2); TIDS(); char* Lw = (char*)lds_raw;
;                     const bf16_t* Wq_ = (const bf16_t*)(w2 + WS_WUQ) + (size_t)l * 384 * 192 + (size_t)hh * 96 * 192; const bf16_t* Wkv_ = (const bf16_t*)(w2 + WS_WUKV) + (size_t)l * 512 * 128 + (size_t)hh * 128 * 128;
;                     __syncthreads();
; #pragma unroll
;                     for (int i_ = 0; i_ < 9; ++i_) { const int c = tid + 512 * i_;
;                         if (c < 2304) { const int row = c / 24, ch = c - row * 24; *(u32x4*)(Lw + row * 400 + ch * 16) = *(const u32x4*)(Wq_ + row * 192 + ch * 8); }
;                         else if (c < 4352) { const int c2 = c - 2304, row = c2 >> 4, ch = c2 & 15; *(u32x4*)(Lw + 38400 + row * 288 + ch * 16) = *(const u32x4*)(Wkv_ + row * 128 + ch * 8); } }
.LBB0_444:
	s_mov_b64 s[4:5], s[86:87]
	s_mul_i32 s6, s2, 0x24000
	s_add_u32 s6, s4, s6
	s_addc_u32 s7, s5, 0
	s_mul_i32 s9, s16, 0x9000
	s_mul_hi_u32 s8, s16, 0x9000
	s_add_u32 s6, s6, s9
	s_addc_u32 s7, s7, s8
	s_add_u32 s6, s6, 0x4400000
	s_addc_u32 s7, s7, 0
	s_add_u32 s10, s4, s14
	s_waitcnt vmcnt(0)
	v_mov_b32_e32 v0, v240
	s_addc_u32 s11, s5, s15
	s_lshl_b64 s[8:9], s[16:17], 15
	s_add_u32 s8, s10, s8
	v_and_b32_e32 v1, 15, v0
	s_addc_u32 s9, s11, s9
	v_lshlrev_b32_e32 v192, 4, v1
	v_lshl_add_u64 v[2:3], s[8:9], 0, v[192:193]
	s_mov_b64 s[8:9], 0x4448000
	v_lshl_add_u64 v[4:5], v[2:3], 0, s[8:9]
	s_movk_i32 s8, 0x8ff
	v_readfirstlane_b32 s20, v0
	v_add_u32_e32 v2, 0, v192
	v_cmp_lt_i32_e32 vcc, s8, v0
	s_waitcnt lgkmcnt(0)
	s_barrier
	s_movk_i32 s8, 0x8ff
	v_mov_b32_e32 v6, v0
	v_cmp_lt_i32_e32 vcc, s8, v0
	s_and_saveexec_b64 s[8:9], vcc
	s_xor_b64 s[8:9], exec, s[8:9]
	s_cbranch_execz .Lmla0_0_a
	v_cmp_gt_u32_e32 vcc, s21, v6
	s_and_saveexec_b64 s[10:11], vcc
	s_cbranch_execz .Lmla0_0_b
	v_add_u32_e32 v3, 0xfffff700, v0
	v_lshrrev_b32_e32 v3, 4, v3
	v_lshlrev_b32_e32 v6, 8, v3
	v_mov_b32_e32 v7, v193
	v_lshl_add_u64 v[6:7], v[4:5], 0, v[6:7]
	global_load_dwordx4 v[12:15], v[6:7], off

; __global__ void __launch_bounds__(NTHR, 2) mega_fwd(Args a) {
;     ...
; #pragma unroll
;                     for (int i_ = 0; i_ < 9; ++i_) { const int c = tid + 512 * i_;
;                         if (c < 2304) { const int row = c / 24, ch = c - row * 24; *(u32x4*)(Lw + row * 400 + ch * 16) = *(const u32x4*)(Wq_ + row * 192 + ch * 8); }
;                         else if (c < 4352) { const int c2 = c - 2304, row = c2 >> 4, ch = c2 & 15; *(u32x4*)(Lw + 38400 + row * 288 + ch * 16) = *(const u32x4*)(Wkv_ + row * 128 + ch * 8); } }
.Lmla0_0_a:
	s_andn2_saveexec_b64 s[8:9], s[8:9]
	s_cbranch_execz .Lmla0_0_c
	v_mul_hi_i32 v3, v6, s95
	v_lshrrev_b32_e32 v7, 31, v3
	v_ashrrev_i32_e32 v3, 2, v3
	v_add_u32_e32 v3, v3, v7
	v_mad_u64_u32 v[10:11], s[10:11], v3, s96, v[6:7]
	v_mul_lo_u32 v6, v3, s18
	v_ashrrev_i32_e32 v7, 31, v6
	v_lshlrev_b32_e32 v8, 3, v10
	v_lshl_add_u64 v[6:7], v[6:7], 1, s[6:7]
	v_ashrrev_i32_e32 v9, 31, v8
	v_lshl_add_u64 v[6:7], v[8:9], 1, v[6:7]
	global_load_dwordx4 v[12:15], v[6:7], off
.Lmla0_0_c:
	s_or_b64 exec, exec, s[8:9]
	s_movk_i32 s8, 0x6ff
	v_add_u32_e32 v6, 0x200, v0
	v_cmp_lt_i32_e32 vcc, s8, v0
	s_and_saveexec_b64 s[8:9], vcc
	s_xor_b64 s[8:9], exec, s[8:9]
	s_cbranch_execz .Lmla0_1_a
	v_cmp_gt_u32_e32 vcc, s21, v6
	s_and_saveexec_b64 s[10:11], vcc
	s_cbranch_execz .Lmla0_1_b
	v_add_u32_e32 v3, 0xfffff900, v0
	v_lshrrev_b32_e32 v3, 4, v3
	v_lshlrev_b32_e32 v6, 8, v3
	v_mov_b32_e32 v7, v193
	v_lshl_add_u64 v[6:7], v[4:5], 0, v[6:7]
	global_load_dwordx4 v[16:19], v[6:7], off

; __global__ void __launch_bounds__(NTHR, 2) mega_fwd(Args a) {
;     ...
; #pragma unroll
;                     for (int i_ = 0; i_ < 9; ++i_) { const int c = tid + 512 * i_;
;                         if (c < 2304) { const int row = c / 24, ch = c - row * 24; *(u32x4*)(Lw + row * 400 + ch * 16) = *(const u32x4*)(Wq_ + row * 192 + ch * 8); }
;                         else if (c < 4352) { const int c2 = c - 2304, row = c2 >> 4, ch = c2 & 15; *(u32x4*)(Lw + 38400 + row * 288 + ch * 16) = *(const u32x4*)(Wkv_ + row * 128 + ch * 8); } }
.Lmla0_1_a:
	s_andn2_saveexec_b64 s[8:9], s[8:9]
	s_cbranch_execz .Lmla0_1_c
	v_mul_hi_i32 v3, v6, s95
	v_lshrrev_b32_e32 v7, 31, v3
	v_ashrrev_i32_e32 v3, 2, v3
	v_add_u32_e32 v3, v3, v7
	v_mad_u64_u32 v[10:11], s[10:11], v3, s96, v[6:7]
	v_mul_lo_u32 v6, v3, s18
	v_ashrrev_i32_e32 v7, 31, v6
	v_lshlrev_b32_e32 v8, 3, v10
	v_lshl_add_u64 v[6:7], v[6:7], 1, s[6:7]
	v_ashrrev_i32_e32 v9, 31, v8
	v_lshl_add_u64 v[6:7], v[8:9], 1, v[6:7]
	global_load_dwordx4 v[16:19], v[6:7], off
.Lmla0_1_c:
	s_or_b64 exec, exec, s[8:9]
	s_movk_i32 s8, 0x4ff
	v_add_u32_e32 v6, 0x400, v0
	v_cmp_lt_i32_e32 vcc, s8, v0
	s_and_saveexec_b64 s[8:9], vcc
	s_xor_b64 s[8:9], exec, s[8:9]
	s_cbranch_execz .Lmla0_2_a
	v_cmp_gt_u32_e32 vcc, s21, v6
	s_and_saveexec_b64 s[10:11], vcc
	s_cbranch_execz .Lmla0_2_b
	v_add_u32_e32 v3, 0xfffffb00, v0
	v_lshrrev_b32_e32 v3, 4, v3
	v_lshlrev_b32_e32 v6, 8, v3
	v_mov_b32_e32 v7, v193
	v_lshl_add_u64 v[6:7], v[4:5], 0, v[6:7]
	global_load_dwordx4 v[20:23], v[6:7], off

; __global__ void __launch_bounds__(NTHR, 2) mega_fwd(Args a) {
;     ...
; #pragma unroll
;                     for (int i_ = 0; i_ < 9; ++i_) { const int c = tid + 512 * i_;
;                         if (c < 2304) { const int row = c / 24, ch = c - row * 24; *(u32x4*)(Lw + row * 400 + ch * 16) = *(const u32x4*)(Wq_ + row * 192 + ch * 8); }
;                         else if (c < 4352) { const int c2 = c - 2304, row = c2 >> 4, ch = c2 & 15; *(u32x4*)(Lw + 38400 + row * 288 + ch * 16) = *(const u32x4*)(Wkv_ + row * 128 + ch * 8); } }
.Lmla0_2_a:
	s_andn2_saveexec_b64 s[8:9], s[8:9]
	s_cbranch_execz .Lmla0_2_c
	v_mul_hi_i32 v3, v6, s95
	v_lshrrev_b32_e32 v7, 31, v3
	v_ashrrev_i32_e32 v3, 2, v3
	v_add_u32_e32 v3, v3, v7
	v_mad_u64_u32 v[10:11], s[10:11], v3, s96, v[6:7]
	v_mul_lo_u32 v6, v3, s18
	v_ashrrev_i32_e32 v7, 31, v6
	v_lshlrev_b32_e32 v8, 3, v10
	v_lshl_add_u64 v[6:7], v[6:7], 1, s[6:7]
	v_ashrrev_i32_e32 v9, 31, v8
	v_lshl_add_u64 v[6:7], v[8:9], 1, v[6:7]
	global_load_dwordx4 v[20:23], v[6:7], off
.Lmla0_2_c:
	s_or_b64 exec, exec, s[8:9]
	s_movk_i32 s8, 0x2ff
	v_add_u32_e32 v6, 0x600, v0
	v_cmp_lt_i32_e32 vcc, s8, v0
	s_and_saveexec_b64 s[8:9], vcc
	s_xor_b64 s[8:9], exec, s[8:9]
	s_cbranch_execz .Lmla0_3_a
	v_cmp_gt_u32_e32 vcc, s21, v6
	s_and_saveexec_b64 s[10:11], vcc
	s_cbranch_execz .Lmla0_3_b
	v_add_u32_e32 v3, 0xfffffd00, v0
	v_lshrrev_b32_e32 v3, 4, v3
	v_lshlrev_b32_e32 v6, 8, v3
	v_mov_b32_e32 v7, v193
	v_lshl_add_u64 v[6:7], v[4:5], 0, v[6:7]
	global_load_dwordx4 v[24:27], v[6:7], off

; __global__ void __launch_bounds__(NTHR, 2) mega_fwd(Args a) {
;     ...
; #pragma unroll
;                     for (int i_ = 0; i_ < 9; ++i_) { const int c = tid + 512 * i_;
;                         if (c < 2304) { const int row = c / 24, ch = c - row * 24; *(u32x4*)(Lw + row * 400 + ch * 16) = *(const u32x4*)(Wq_ + row * 192 + ch * 8); }
;                         else if (c < 4352) { const int c2 = c - 2304, row = c2 >> 4, ch = c2 & 15; *(u32x4*)(Lw + 38400 + row * 288 + ch * 16) = *(const u32x4*)(Wkv_ + row * 128 + ch * 8); } }
.Lmla0_3_a:
	s_andn2_saveexec_b64 s[8:9], s[8:9]
	s_cbranch_execz .Lmla0_3_c
	v_mul_hi_i32 v3, v6, s95
	v_lshrrev_b32_e32 v7, 31, v3
	v_ashrrev_i32_e32 v3, 2, v3
	v_add_u32_e32 v3, v3, v7
	v_mad_u64_u32 v[10:11], s[10:11], v3, s96, v[6:7]
	v_mul_lo_u32 v6, v3, s18
	v_ashrrev_i32_e32 v7, 31, v6
	v_lshlrev_b32_e32 v8, 3, v10
	v_lshl_add_u64 v[6:7], v[6:7], 1, s[6:7]
	v_ashrrev_i32_e32 v9, 31, v8
	v_lshl_add_u64 v[6:7], v[8:9], 1, v[6:7]
	global_load_dwordx4 v[24:27], v[6:7], off
.Lmla0_3_c:
	s_or_b64 exec, exec, s[8:9]
	s_movk_i32 s8, 0xff
	v_add_u32_e32 v6, 0x800, v0
	v_cmp_lt_i32_e32 vcc, s8, v0
	s_and_saveexec_b64 s[8:9], vcc
	s_xor_b64 s[8:9], exec, s[8:9]
	s_cbranch_execz .Lmla0_4_a
	v_cmp_gt_u32_e32 vcc, s21, v6
	s_and_saveexec_b64 s[10:11], vcc
	s_cbranch_execz .Lmla0_4_b
	v_add_u32_e32 v3, 0xffffff00, v0
	v_lshrrev_b32_e32 v3, 4, v3
	v_lshlrev_b32_e32 v6, 8, v3
	v_mov_b32_e32 v7, v193
	v_lshl_add_u64 v[6:7], v[4:5], 0, v[6:7]
	global_load_dwordx4 v[28:31], v[6:7], off

; __global__ void __launch_bounds__(NTHR, 2) mega_fwd(Args a) {
;     ...
; #pragma unroll
;                     for (int i_ = 0; i_ < 9; ++i_) { const int c = tid + 512 * i_;
;                         if (c < 2304) { const int row = c / 24, ch = c - row * 24; *(u32x4*)(Lw + row * 400 + ch * 16) = *(const u32x4*)(Wq_ + row * 192 + ch * 8); }
;                         else if (c < 4352) { const int c2 = c - 2304, row = c2 >> 4, ch = c2 & 15; *(u32x4*)(Lw + 38400 + row * 288 + ch * 16) = *(const u32x4*)(Wkv_ + row * 128 + ch * 8); } }
.Lmla0_4_a:
	s_andn2_saveexec_b64 s[8:9], s[8:9]
	s_cbranch_execz .Lmla0_4_c
	v_mul_hi_i32 v3, v6, s95
	v_lshrrev_b32_e32 v7, 31, v3
	v_ashrrev_i32_e32 v3, 2, v3
	v_add_u32_e32 v3, v3, v7
	v_mad_u64_u32 v[10:11], s[10:11], v3, s96, v[6:7]
	v_mul_lo_u32 v6, v3, s18
	v_ashrrev_i32_e32 v7, 31, v6
	v_lshlrev_b32_e32 v8, 3, v10
	v_lshl_add_u64 v[6:7], v[6:7], 1, s[6:7]
	v_ashrrev_i32_e32 v9, 31, v8
	v_lshl_add_u64 v[6:7], v[8:9], 1, v[6:7]
	global_load_dwordx4 v[28:31], v[6:7], off
.Lmla0_4_c:
	s_or_b64 exec, exec, s[8:9]
	s_movk_i32 s8, 0xfeff
	v_add_u32_e32 v6, 0xa00, v0
	v_cmp_lt_i32_e32 vcc, s8, v0
	s_and_saveexec_b64 s[8:9], vcc
	s_xor_b64 s[8:9], exec, s[8:9]
	s_cbranch_execz .Lmla0_5_a
	v_cmp_gt_u32_e32 vcc, s21, v6
	s_and_saveexec_b64 s[10:11], vcc
	s_cbranch_execz .Lmla0_5_b
	v_add_u32_e32 v3, 0x100, v0
	v_lshrrev_b32_e32 v3, 4, v3
	v_lshlrev_b32_e32 v6, 8, v3
	v_mov_b32_e32 v7, v193
	v_lshl_add_u64 v[6:7], v[4:5], 0, v[6:7]
	global_load_dwordx4 v[32:35], v[6:7], off

; __global__ void __launch_bounds__(NTHR, 2) mega_fwd(Args a) {
;     ...
; #pragma unroll
;                     for (int i_ = 0; i_ < 9; ++i_) { const int c = tid + 512 * i_;
;                         if (c < 2304) { const int row = c / 24, ch = c - row * 24; *(u32x4*)(Lw + row * 400 + ch * 16) = *(const u32x4*)(Wq_ + row * 192 + ch * 8); }
;                         else if (c < 4352) { const int c2 = c - 2304, row = c2 >> 4, ch = c2 & 15; *(u32x4*)(Lw + 38400 + row * 288 + ch * 16) = *(const u32x4*)(Wkv_ + row * 128 + ch * 8); } }
.Lmla0_5_a:
	s_andn2_saveexec_b64 s[8:9], s[8:9]
	s_cbranch_execz .Lmla0_5_c
	v_mul_hi_i32 v3, v6, s95
	v_lshrrev_b32_e32 v7, 31, v3
	v_ashrrev_i32_e32 v3, 2, v3
	v_add_u32_e32 v3, v3, v7
	v_mad_u64_u32 v[10:11], s[10:11], v3, s96, v[6:7]
	v_mul_lo_u32 v6, v3, s18
	v_ashrrev_i32_e32 v7, 31, v6
	v_lshlrev_b32_e32 v8, 3, v10
	v_lshl_add_u64 v[6:7], v[6:7], 1, s[6:7]
	v_ashrrev_i32_e32 v9, 31, v8
	v_lshl_add_u64 v[6:7], v[8:9], 1, v[6:7]
	global_load_dwordx4 v[32:35], v[6:7], off
.Lmla0_5_c:
	s_or_b64 exec, exec, s[8:9]
	s_movk_i32 s8, 0xfcff
	v_add_u32_e32 v6, 0xc00, v0
	v_cmp_lt_i32_e32 vcc, s8, v0
	s_and_saveexec_b64 s[8:9], vcc
	s_xor_b64 s[8:9], exec, s[8:9]
	s_cbranch_execz .Lmla0_6_a
	v_cmp_gt_u32_e32 vcc, s21, v6
	s_and_saveexec_b64 s[10:11], vcc
	s_cbranch_execz .Lmla0_6_b
	v_add_u32_e32 v3, 0x300, v0
	v_lshrrev_b32_e32 v3, 4, v3
	v_lshlrev_b32_e32 v6, 8, v3
	v_mov_b32_e32 v7, v193
	v_lshl_add_u64 v[6:7], v[4:5], 0, v[6:7]
	global_load_dwordx4 v[36:39], v[6:7], off

; __global__ void __launch_bounds__(NTHR, 2) mega_fwd(Args a) {
;     ...
; #pragma unroll
;                     for (int i_ = 0; i_ < 9; ++i_) { const int c = tid + 512 * i_;
;                         if (c < 2304) { const int row = c / 24, ch = c - row * 24; *(u32x4*)(Lw + row * 400 + ch * 16) = *(const u32x4*)(Wq_ + row * 192 + ch * 8); }
;                         else if (c < 4352) { const int c2 = c - 2304, row = c2 >> 4, ch = c2 & 15; *(u32x4*)(Lw + 38400 + row * 288 + ch * 16) = *(const u32x4*)(Wkv_ + row * 128 + ch * 8); } }
.Lmla0_6_a:
	s_andn2_saveexec_b64 s[8:9], s[8:9]
	s_cbranch_execz .Lmla0_6_c
	v_mul_hi_i32 v3, v6, s95
	v_lshrrev_b32_e32 v7, 31, v3
	v_ashrrev_i32_e32 v3, 2, v3
	v_add_u32_e32 v3, v3, v7
	v_mad_u64_u32 v[10:11], s[10:11], v3, s96, v[6:7]
	v_mul_lo_u32 v6, v3, s18
	v_ashrrev_i32_e32 v7, 31, v6
	v_lshlrev_b32_e32 v8, 3, v10
	v_lshl_add_u64 v[6:7], v[6:7], 1, s[6:7]
	v_ashrrev_i32_e32 v9, 31, v8
	v_lshl_add_u64 v[6:7], v[8:9], 1, v[6:7]
	global_load_dwordx4 v[36:39], v[6:7], off
.Lmla0_6_c:
	s_or_b64 exec, exec, s[8:9]
	s_movk_i32 s8, 0xfaff
	v_add_u32_e32 v6, 0xe00, v0
	v_cmp_lt_i32_e32 vcc, s8, v0
	s_and_saveexec_b64 s[8:9], vcc
	s_xor_b64 s[8:9], exec, s[8:9]
	s_cbranch_execz .Lmla0_7_a
	v_cmp_gt_u32_e32 vcc, s21, v6
	s_and_saveexec_b64 s[10:11], vcc
	s_cbranch_execz .Lmla0_7_b
	v_add_u32_e32 v3, 0x500, v0
	v_lshrrev_b32_e32 v3, 4, v3
	v_lshlrev_b32_e32 v6, 8, v3
	v_mov_b32_e32 v7, v193
	v_lshl_add_u64 v[6:7], v[4:5], 0, v[6:7]
	global_load_dwordx4 v[40:43], v[6:7], off

; __global__ void __launch_bounds__(NTHR, 2) mega_fwd(Args a) {
;     ...
; #pragma unroll
;                     for (int i_ = 0; i_ < 9; ++i_) { const int c = tid + 512 * i_;
;                         if (c < 2304) { const int row = c / 24, ch = c - row * 24; *(u32x4*)(Lw + row * 400 + ch * 16) = *(const u32x4*)(Wq_ + row * 192 + ch * 8); }
;                         else if (c < 4352) { const int c2 = c - 2304, row = c2 >> 4, ch = c2 & 15; *(u32x4*)(Lw + 38400 + row * 288 + ch * 16) = *(const u32x4*)(Wkv_ + row * 128 + ch * 8); } }
.Lmla0_7_a:
	s_andn2_saveexec_b64 s[8:9], s[8:9]
	s_cbranch_execz .Lmla0_7_c
	v_mul_hi_i32 v3, v6, s95
	v_lshrrev_b32_e32 v7, 31, v3
	v_ashrrev_i32_e32 v3, 2, v3
	v_add_u32_e32 v3, v3, v7
	v_mad_u64_u32 v[10:11], s[10:11], v3, s96, v[6:7]
	v_mul_lo_u32 v6, v3, s18
	v_ashrrev_i32_e32 v7, 31, v6
	v_lshlrev_b32_e32 v8, 3, v10
	v_lshl_add_u64 v[6:7], v[6:7], 1, s[6:7]
	v_ashrrev_i32_e32 v9, 31, v8
	v_lshl_add_u64 v[6:7], v[8:9], 1, v[6:7]
	global_load_dwordx4 v[40:43], v[6:7], off
.Lmla0_7_c:
	s_or_b64 exec, exec, s[8:9]
	s_movk_i32 s8, 0xf8ff
	v_add_u32_e32 v6, 0x1000, v0
	v_cmp_lt_i32_e32 vcc, s8, v0
	s_and_saveexec_b64 s[8:9], vcc
	s_xor_b64 s[8:9], exec, s[8:9]
	s_cbranch_execz .Lmla0_8_a
	v_cmp_gt_u32_e32 vcc, s21, v6
	s_and_saveexec_b64 s[10:11], vcc
	s_cbranch_execz .Lmla0_8_b
	v_add_u32_e32 v3, 0x700, v0
	v_lshrrev_b32_e32 v3, 4, v3
	v_lshlrev_b32_e32 v6, 8, v3
	v_mov_b32_e32 v7, v193
	v_lshl_add_u64 v[6:7], v[4:5], 0, v[6:7]
	global_load_dwordx4 v[44:47], v[6:7], off

; __global__ void __launch_bounds__(NTHR, 2) mega_fwd(Args a) {
;     ...
; #pragma unroll
;                     for (int i_ = 0; i_ < 9; ++i_) { const int c = tid + 512 * i_;
;                         if (c < 2304) { const int row = c / 24, ch = c - row * 24; *(u32x4*)(Lw + row * 400 + ch * 16) = *(const u32x4*)(Wq_ + row * 192 + ch * 8); }
;                         else if (c < 4352) { const int c2 = c - 2304, row = c2 >> 4, ch = c2 & 15; *(u32x4*)(Lw + 38400 + row * 288 + ch * 16) = *(const u32x4*)(Wkv_ + row * 128 + ch * 8); } }
.Lmla0_8_a:
	s_andn2_saveexec_b64 s[8:9], s[8:9]
	s_cbranch_execz .Lmla0_8_c
	v_mul_hi_i32 v3, v6, s95
	v_lshrrev_b32_e32 v7, 31, v3
	v_ashrrev_i32_e32 v3, 2, v3
	v_add_u32_e32 v3, v3, v7
	v_mad_u64_u32 v[10:11], s[10:11], v3, s96, v[6:7]
	v_mul_lo_u32 v6, v3, s18
	v_ashrrev_i32_e32 v7, 31, v6
	v_lshlrev_b32_e32 v8, 3, v10
	v_lshl_add_u64 v[6:7], v[6:7], 1, s[6:7]
	v_ashrrev_i32_e32 v9, 31, v8
	v_lshl_add_u64 v[6:7], v[8:9], 1, v[6:7]
	global_load_dwordx4 v[44:47], v[6:7], off
.Lmla0_8_c:
	s_or_b64 exec, exec, s[8:9]
	s_waitcnt vmcnt(0)
	s_movk_i32 s8, 0x8ff
	v_mov_b32_e32 v6, v0
	v_cmp_lt_i32_e32 vcc, s8, v0
	s_and_saveexec_b64 s[8:9], vcc
	s_xor_b64 s[8:9], exec, s[8:9]
	s_cbranch_execz .Lmla1_0_a
	v_cmp_gt_u32_e32 vcc, s21, v6
	s_and_saveexec_b64 s[10:11], vcc
	s_cbranch_execz .Lmla1_0_b
	v_add_u32_e32 v3, 0xfffff700, v0
	v_lshrrev_b32_e32 v3, 4, v3
	v_mad_u64_u32 v[10:11], s[22:23], v3, s28, v[2:3]
	ds_write_b128 v10, v[12:15] offset:38400

; __global__ void __launch_bounds__(NTHR, 2) mega_fwd(Args a) {
;     ...
; #pragma unroll
;                     for (int i_ = 0; i_ < 9; ++i_) { const int c = tid + 512 * i_;
;                         if (c < 2304) { const int row = c / 24, ch = c - row * 24; *(u32x4*)(Lw + row * 400 + ch * 16) = *(const u32x4*)(Wq_ + row * 192 + ch * 8); }
;                         else if (c < 4352) { const int c2 = c - 2304, row = c2 >> 4, ch = c2 & 15; *(u32x4*)(Lw + 38400 + row * 288 + ch * 16) = *(const u32x4*)(Wkv_ + row * 128 + ch * 8); } }
.Lmla1_0_a:
	s_andn2_saveexec_b64 s[8:9], s[8:9]
	s_cbranch_execz .Lmla1_0_c
	v_mul_hi_i32 v3, v6, s95
	v_lshrrev_b32_e32 v7, 31, v3
	v_ashrrev_i32_e32 v3, 2, v3
	v_add_u32_e32 v3, v3, v7
	v_mad_u64_u32 v[10:11], s[10:11], v3, s96, v[6:7]
	v_mul_lo_u32 v3, v3, s52
	v_lshlrev_b32_e32 v10, 4, v10
	v_add3_u32 v3, 0, v3, v10
	ds_write_b128 v3, v[12:15]
.Lmla1_0_c:
	s_or_b64 exec, exec, s[8:9]
	s_movk_i32 s8, 0x6ff
	v_add_u32_e32 v6, 0x200, v0
	v_cmp_lt_i32_e32 vcc, s8, v0
	s_and_saveexec_b64 s[8:9], vcc
	s_xor_b64 s[8:9], exec, s[8:9]
	s_cbranch_execz .Lmla1_1_a
	v_cmp_gt_u32_e32 vcc, s21, v6
	s_and_saveexec_b64 s[10:11], vcc
	s_cbranch_execz .Lmla1_1_b
	v_add_u32_e32 v3, 0xfffff900, v0
	v_lshrrev_b32_e32 v3, 4, v3
	v_mad_u64_u32 v[10:11], s[22:23], v3, s28, v[2:3]
	ds_write_b128 v10, v[16:19] offset:38400

; __global__ void __launch_bounds__(NTHR, 2) mega_fwd(Args a) {
;     ...
; #pragma unroll
;                     for (int i_ = 0; i_ < 9; ++i_) { const int c = tid + 512 * i_;
;                         if (c < 2304) { const int row = c / 24, ch = c - row * 24; *(u32x4*)(Lw + row * 400 + ch * 16) = *(const u32x4*)(Wq_ + row * 192 + ch * 8); }
;                         else if (c < 4352) { const int c2 = c - 2304, row = c2 >> 4, ch = c2 & 15; *(u32x4*)(Lw + 38400 + row * 288 + ch * 16) = *(const u32x4*)(Wkv_ + row * 128 + ch * 8); } }
.Lmla1_1_a:
	s_andn2_saveexec_b64 s[8:9], s[8:9]
	s_cbranch_execz .Lmla1_1_c
	v_mul_hi_i32 v3, v6, s95
	v_lshrrev_b32_e32 v7, 31, v3
	v_ashrrev_i32_e32 v3, 2, v3
	v_add_u32_e32 v3, v3, v7
	v_mad_u64_u32 v[10:11], s[10:11], v3, s96, v[6:7]
	v_mul_lo_u32 v3, v3, s52
	v_lshlrev_b32_e32 v10, 4, v10
	v_add3_u32 v3, 0, v3, v10
	ds_write_b128 v3, v[16:19]
.Lmla1_1_c:
	s_or_b64 exec, exec, s[8:9]
	s_movk_i32 s8, 0x4ff
	v_add_u32_e32 v6, 0x400, v0
	v_cmp_lt_i32_e32 vcc, s8, v0
	s_and_saveexec_b64 s[8:9], vcc
	s_xor_b64 s[8:9], exec, s[8:9]
	s_cbranch_execz .Lmla1_2_a
	v_cmp_gt_u32_e32 vcc, s21, v6
	s_and_saveexec_b64 s[10:11], vcc
	s_cbranch_execz .Lmla1_2_b
	v_add_u32_e32 v3, 0xfffffb00, v0
	v_lshrrev_b32_e32 v3, 4, v3
	v_mad_u64_u32 v[10:11], s[22:23], v3, s28, v[2:3]
	ds_write_b128 v10, v[20:23] offset:38400

; __global__ void __launch_bounds__(NTHR, 2) mega_fwd(Args a) {
;     ...
; #pragma unroll
;                     for (int i_ = 0; i_ < 9; ++i_) { const int c = tid + 512 * i_;
;                         if (c < 2304) { const int row = c / 24, ch = c - row * 24; *(u32x4*)(Lw + row * 400 + ch * 16) = *(const u32x4*)(Wq_ + row * 192 + ch * 8); }
;                         else if (c < 4352) { const int c2 = c - 2304, row = c2 >> 4, ch = c2 & 15; *(u32x4*)(Lw + 38400 + row * 288 + ch * 16) = *(const u32x4*)(Wkv_ + row * 128 + ch * 8); } }
.Lmla1_2_a:
	s_andn2_saveexec_b64 s[8:9], s[8:9]
	s_cbranch_execz .Lmla1_2_c
	v_mul_hi_i32 v3, v6, s95
	v_lshrrev_b32_e32 v7, 31, v3
	v_ashrrev_i32_e32 v3, 2, v3
	v_add_u32_e32 v3, v3, v7
	v_mad_u64_u32 v[10:11], s[10:11], v3, s96, v[6:7]
	v_mul_lo_u32 v3, v3, s52
	v_lshlrev_b32_e32 v10, 4, v10
	v_add3_u32 v3, 0, v3, v10
	ds_write_b128 v3, v[20:23]
.Lmla1_2_c:
	s_or_b64 exec, exec, s[8:9]
	s_movk_i32 s8, 0x2ff
	v_add_u32_e32 v6, 0x600, v0
	v_cmp_lt_i32_e32 vcc, s8, v0
	s_and_saveexec_b64 s[8:9], vcc
	s_xor_b64 s[8:9], exec, s[8:9]
	s_cbranch_execz .Lmla1_3_a
	v_cmp_gt_u32_e32 vcc, s21, v6
	s_and_saveexec_b64 s[10:11], vcc
	s_cbranch_execz .Lmla1_3_b
	v_add_u32_e32 v3, 0xfffffd00, v0
	v_lshrrev_b32_e32 v3, 4, v3
	v_mad_u64_u32 v[10:11], s[22:23], v3, s28, v[2:3]
	ds_write_b128 v10, v[24:27] offset:38400

; __global__ void __launch_bounds__(NTHR, 2) mega_fwd(Args a) {
;     ...
; #pragma unroll
;                     for (int i_ = 0; i_ < 9; ++i_) { const int c = tid + 512 * i_;
;                         if (c < 2304) { const int row = c / 24, ch = c - row * 24; *(u32x4*)(Lw + row * 400 + ch * 16) = *(const u32x4*)(Wq_ + row * 192 + ch * 8); }
;                         else if (c < 4352) { const int c2 = c - 2304, row = c2 >> 4, ch = c2 & 15; *(u32x4*)(Lw + 38400 + row * 288 + ch * 16) = *(const u32x4*)(Wkv_ + row * 128 + ch * 8); } }
.Lmla1_3_a:
	s_andn2_saveexec_b64 s[8:9], s[8:9]
	s_cbranch_execz .Lmla1_3_c
	v_mul_hi_i32 v3, v6, s95
	v_lshrrev_b32_e32 v7, 31, v3
	v_ashrrev_i32_e32 v3, 2, v3
	v_add_u32_e32 v3, v3, v7
	v_mad_u64_u32 v[10:11], s[10:11], v3, s96, v[6:7]
	v_mul_lo_u32 v3, v3, s52
	v_lshlrev_b32_e32 v10, 4, v10
	v_add3_u32 v3, 0, v3, v10
	ds_write_b128 v3, v[24:27]
.Lmla1_3_c:
	s_or_b64 exec, exec, s[8:9]
	s_movk_i32 s8, 0xff
	v_add_u32_e32 v6, 0x800, v0
	v_cmp_lt_i32_e32 vcc, s8, v0
	s_and_saveexec_b64 s[8:9], vcc
	s_xor_b64 s[8:9], exec, s[8:9]
	s_cbranch_execz .Lmla1_4_a
	v_cmp_gt_u32_e32 vcc, s21, v6
	s_and_saveexec_b64 s[10:11], vcc
	s_cbranch_execz .Lmla1_4_b
	v_add_u32_e32 v3, 0xffffff00, v0
	v_lshrrev_b32_e32 v3, 4, v3
	v_mad_u64_u32 v[10:11], s[22:23], v3, s28, v[2:3]
	ds_write_b128 v10, v[28:31] offset:38400

; __global__ void __launch_bounds__(NTHR, 2) mega_fwd(Args a) {
;     ...
; #pragma unroll
;                     for (int i_ = 0; i_ < 9; ++i_) { const int c = tid + 512 * i_;
;                         if (c < 2304) { const int row = c / 24, ch = c - row * 24; *(u32x4*)(Lw + row * 400 + ch * 16) = *(const u32x4*)(Wq_ + row * 192 + ch * 8); }
;                         else if (c < 4352) { const int c2 = c - 2304, row = c2 >> 4, ch = c2 & 15; *(u32x4*)(Lw + 38400 + row * 288 + ch * 16) = *(const u32x4*)(Wkv_ + row * 128 + ch * 8); } }
.Lmla1_4_a:
	s_andn2_saveexec_b64 s[8:9], s[8:9]
	s_cbranch_execz .Lmla1_4_c
	v_mul_hi_i32 v3, v6, s95
	v_lshrrev_b32_e32 v7, 31, v3
	v_ashrrev_i32_e32 v3, 2, v3
	v_add_u32_e32 v3, v3, v7
	v_mad_u64_u32 v[10:11], s[10:11], v3, s96, v[6:7]
	v_mul_lo_u32 v3, v3, s52
	v_lshlrev_b32_e32 v10, 4, v10
	v_add3_u32 v3, 0, v3, v10
	ds_write_b128 v3, v[28:31]
.Lmla1_4_c:
	s_or_b64 exec, exec, s[8:9]
	s_movk_i32 s8, 0xfeff
	v_add_u32_e32 v6, 0xa00, v0
	v_cmp_lt_i32_e32 vcc, s8, v0
	s_and_saveexec_b64 s[8:9], vcc
	s_xor_b64 s[8:9], exec, s[8:9]
	s_cbranch_execz .Lmla1_5_a
	v_cmp_gt_u32_e32 vcc, s21, v6
	s_and_saveexec_b64 s[10:11], vcc
	s_cbranch_execz .Lmla1_5_b
	v_add_u32_e32 v3, 0x100, v0
	v_lshrrev_b32_e32 v3, 4, v3
	v_mad_u64_u32 v[10:11], s[22:23], v3, s28, v[2:3]
	ds_write_b128 v10, v[32:35] offset:38400

; __global__ void __launch_bounds__(NTHR, 2) mega_fwd(Args a) {
;     ...
; #pragma unroll
;                     for (int i_ = 0; i_ < 9; ++i_) { const int c = tid + 512 * i_;
;                         if (c < 2304) { const int row = c / 24, ch = c - row * 24; *(u32x4*)(Lw + row * 400 + ch * 16) = *(const u32x4*)(Wq_ + row * 192 + ch * 8); }
;                         else if (c < 4352) { const int c2 = c - 2304, row = c2 >> 4, ch = c2 & 15; *(u32x4*)(Lw + 38400 + row * 288 + ch * 16) = *(const u32x4*)(Wkv_ + row * 128 + ch * 8); } }
.Lmla1_5_a:
	s_andn2_saveexec_b64 s[8:9], s[8:9]
	s_cbranch_execz .Lmla1_5_c
	v_mul_hi_i32 v3, v6, s95
	v_lshrrev_b32_e32 v7, 31, v3
	v_ashrrev_i32_e32 v3, 2, v3
	v_add_u32_e32 v3, v3, v7
	v_mad_u64_u32 v[10:11], s[10:11], v3, s96, v[6:7]
	v_mul_lo_u32 v3, v3, s52
	v_lshlrev_b32_e32 v10, 4, v10
	v_add3_u32 v3, 0, v3, v10
	ds_write_b128 v3, v[32:35]
.Lmla1_5_c:
	s_or_b64 exec, exec, s[8:9]
	s_movk_i32 s8, 0xfcff
	v_add_u32_e32 v6, 0xc00, v0
	v_cmp_lt_i32_e32 vcc, s8, v0
	s_and_saveexec_b64 s[8:9], vcc
	s_xor_b64 s[8:9], exec, s[8:9]
	s_cbranch_execz .Lmla1_6_a
	v_cmp_gt_u32_e32 vcc, s21, v6
	s_and_saveexec_b64 s[10:11], vcc
	s_cbranch_execz .Lmla1_6_b
	v_add_u32_e32 v3, 0x300, v0
	v_lshrrev_b32_e32 v3, 4, v3
	v_mad_u64_u32 v[10:11], s[22:23], v3, s28, v[2:3]
	ds_write_b128 v10, v[36:39] offset:38400

; __global__ void __launch_bounds__(NTHR, 2) mega_fwd(Args a) {
;     ...
; #pragma unroll
;                     for (int i_ = 0; i_ < 9; ++i_) { const int c = tid + 512 * i_;
;                         if (c < 2304) { const int row = c / 24, ch = c - row * 24; *(u32x4*)(Lw + row * 400 + ch * 16) = *(const u32x4*)(Wq_ + row * 192 + ch * 8); }
;                         else if (c < 4352) { const int c2 = c - 2304, row = c2 >> 4, ch = c2 & 15; *(u32x4*)(Lw + 38400 + row * 288 + ch * 16) = *(const u32x4*)(Wkv_ + row * 128 + ch * 8); } }
.Lmla1_6_a:
	s_andn2_saveexec_b64 s[8:9], s[8:9]
	s_cbranch_execz .Lmla1_6_c
	v_mul_hi_i32 v3, v6, s95
	v_lshrrev_b32_e32 v7, 31, v3
	v_ashrrev_i32_e32 v3, 2, v3
	v_add_u32_e32 v3, v3, v7
	v_mad_u64_u32 v[10:11], s[10:11], v3, s96, v[6:7]
	v_mul_lo_u32 v3, v3, s52
	v_lshlrev_b32_e32 v10, 4, v10
	v_add3_u32 v3, 0, v3, v10
	ds_write_b128 v3, v[36:39]
.Lmla1_6_c:
	s_or_b64 exec, exec, s[8:9]
	s_movk_i32 s8, 0xfaff
	v_add_u32_e32 v6, 0xe00, v0
	v_cmp_lt_i32_e32 vcc, s8, v0
	s_and_saveexec_b64 s[8:9], vcc
	s_xor_b64 s[8:9], exec, s[8:9]
	s_cbranch_execz .Lmla1_7_a
	v_cmp_gt_u32_e32 vcc, s21, v6
	s_and_saveexec_b64 s[10:11], vcc
	s_cbranch_execz .Lmla1_7_b
	v_add_u32_e32 v3, 0x500, v0
	v_lshrrev_b32_e32 v3, 4, v3
	v_mad_u64_u32 v[10:11], s[22:23], v3, s28, v[2:3]
	ds_write_b128 v10, v[40:43] offset:38400

; __global__ void __launch_bounds__(NTHR, 2) mega_fwd(Args a) {
;     ...
; #pragma unroll
;                     for (int i_ = 0; i_ < 9; ++i_) { const int c = tid + 512 * i_;
;                         if (c < 2304) { const int row = c / 24, ch = c - row * 24; *(u32x4*)(Lw + row * 400 + ch * 16) = *(const u32x4*)(Wq_ + row * 192 + ch * 8); }
;                         else if (c < 4352) { const int c2 = c - 2304, row = c2 >> 4, ch = c2 & 15; *(u32x4*)(Lw + 38400 + row * 288 + ch * 16) = *(const u32x4*)(Wkv_ + row * 128 + ch * 8); } }
.Lmla1_7_a:
	s_andn2_saveexec_b64 s[8:9], s[8:9]
	s_cbranch_execz .Lmla1_7_c
	v_mul_hi_i32 v3, v6, s95
	v_lshrrev_b32_e32 v7, 31, v3
	v_ashrrev_i32_e32 v3, 2, v3
	v_add_u32_e32 v3, v3, v7
	v_mad_u64_u32 v[10:11], s[10:11], v3, s96, v[6:7]
	v_mul_lo_u32 v3, v3, s52
	v_lshlrev_b32_e32 v10, 4, v10
	v_add3_u32 v3, 0, v3, v10
	ds_write_b128 v3, v[40:43]
.Lmla1_7_c:
	s_or_b64 exec, exec, s[8:9]
	s_movk_i32 s8, 0xf8ff
	v_add_u32_e32 v6, 0x1000, v0
	v_cmp_lt_i32_e32 vcc, s8, v0
	s_and_saveexec_b64 s[8:9], vcc
	s_xor_b64 s[8:9], exec, s[8:9]
	s_cbranch_execz .Lmla1_8_a
	v_cmp_gt_u32_e32 vcc, s21, v6
	s_and_saveexec_b64 s[10:11], vcc
	s_cbranch_execz .Lmla1_8_b
	v_add_u32_e32 v3, 0x700, v0
	v_lshrrev_b32_e32 v3, 4, v3
	v_mad_u64_u32 v[10:11], s[22:23], v3, s28, v[2:3]
	ds_write_b128 v10, v[44:47] offset:38400

; __global__ void __launch_bounds__(NTHR, 2) mega_fwd(Args a) {
;     ...
; #pragma unroll
;                     for (int i_ = 0; i_ < 9; ++i_) { const int c = tid + 512 * i_;
;                         if (c < 2304) { const int row = c / 24, ch = c - row * 24; *(u32x4*)(Lw + row * 400 + ch * 16) = *(const u32x4*)(Wq_ + row * 192 + ch * 8); }
;                         else if (c < 4352) { const int c2 = c - 2304, row = c2 >> 4, ch = c2 & 15; *(u32x4*)(Lw + 38400 + row * 288 + ch * 16) = *(const u32x4*)(Wkv_ + row * 128 + ch * 8); } }
.Lmla1_8_a:
	s_andn2_saveexec_b64 s[8:9], s[8:9]
	s_cbranch_execz .Lmla1_8_c
	v_mul_hi_i32 v3, v6, s95
	v_lshrrev_b32_e32 v7, 31, v3
	v_ashrrev_i32_e32 v3, 2, v3
	v_add_u32_e32 v3, v3, v7
	v_mad_u64_u32 v[10:11], s[10:11], v3, s96, v[6:7]
	v_mul_lo_u32 v3, v3, s52
	v_lshlrev_b32_e32 v10, 4, v10
	v_add3_u32 v3, 0, v3, v10
	ds_write_b128 v3, v[44:47]

; __device__ __forceinline__ unsigned xb_ld(unsigned* p)              { return __hip_atomic_load(p, __ATOMIC_RELAXED, __HIP_MEMORY_SCOPE_AGENT); }
; __device__ __forceinline__ unsigned xb_add(unsigned* p, unsigned v) { return __hip_atomic_fetch_add(p, v, __ATOMIC_RELAXED, __HIP_MEMORY_SCOPE_AGENT); }
; #define XB_SPIN(cond, bar) do { unsigned _sp = 0; while (cond) { __builtin_amdgcn_s_sleep(1); \
;     if ((++_sp & 255u) == 0u) { if (xb_ld(&(bar)[XB_TMO])) break; if (_sp > XB_SPIN_CAP) { atomicAdd(&(bar)[XB_TMO], 1u); break; } } } } while (0)
; #define GSYNC() xcd_barrier(bar)
; __device__ __forceinline__ void xcd_barrier(const XcdBarrier& b) {
;     asm volatile("s_waitcnt vmcnt(0)" ::: "memory");
;     __syncthreads();
;     if (threadIdx.x == 0) {
;         unsigned* bar = b.bar;
;         __builtin_amdgcn_s_waitcnt(0);
;         unsigned nloc = b.st[0], nx = b.st[1];
;         if (nloc == 0u) { xcd_barrier_complete(bar, b.x, nloc, nx); b.st[0] = nloc; b.st[1] = nx; }
;         const unsigned old = xb_add(&bar[XB_XSUB(b.x)], 1u);
;         const unsigned gen = old / nloc;
;         if (old + 1u == (gen + 1u) * nloc) {
;             __builtin_amdgcn_fence(__ATOMIC_RELEASE, "agent");
;             asm volatile("s_waitcnt vmcnt(0)" ::: "memory");
;             const unsigned og = xb_add(&bar[XB_TOP], 1u);
;             const unsigned tg = og / nx;
;             if (og + 1u == (tg + 1u) * nx) xb_add(&bar[XB_TOPGEN], 1u);
;             else XB_SPIN(xb_ld(&bar[XB_TOPGEN]) == tg, bar);
;             __builtin_amdgcn_fence(__ATOMIC_ACQUIRE, "agent");
;             xb_add(&bar[XB_XGEN(b.x)], 1u);
;             asm volatile("s_waitcnt vmcnt(0)" ::: "memory");
;         } else {
;             XB_SPIN(xb_ld(&bar[XB_XGEN(b.x)]) == gen, bar);
;             __builtin_amdgcn_fence(__ATOMIC_ACQUIRE, "agent");
;             asm volatile("s_waitcnt vmcnt(0)" ::: "memory");
;         }
;     }
;     __syncthreads();
; }
; __global__ void __launch_bounds__(NTHR, 2) mega_fwd(Args a) {
;     ...
;             if (l == DEPTH - 1) GSYNC();
.LBB0_1331:
	s_branch .LBB0_200
